# GEMM K-loops (all four): removed the redundant mid-block s_setprio 0/1 pair and the redundant post-barrier lgkmcnt(0) from every 32-MFMA block (issue slots on the barrier-to-MFMA hand-off path)
# speedup vs baseline: 1.0023x; 1.0023x over previous
.LBB0_270:
	s_add_u32 s34, s8, 0xfff80080
	s_addc_u32 s35, s9, -1
	s_and_b64 s[30:31], s[30:31], exec
	s_cselect_b32 s35, s2, s35
	s_cselect_b32 s34, s25, s34
	s_cselect_b32 s31, s23, s55
	s_cselect_b32 s30, s54, s1
	s_add_i32 s57, 0, 0x10000
	v_add_u32_e32 v72, s57, v181
	s_add_i32 s62, 0, 0x14000
	ds_read_b128 v[68:71], v72
	ds_read_b128 v[82:85], v72 offset:1024
	ds_read_b128 v[86:89], v72 offset:2048
	ds_read_b128 v[146:149], v72 offset:3072
	v_add_u32_e32 v72, s62, v181
	ds_read_b128 v[150:153], v72
	ds_read_b128 v[154:157], v72 offset:1024
	ds_read_b128 v[158:161], v72 offset:2048
	ds_read_b128 v[202:205], v72 offset:3072
	v_lshl_add_u64 v[72:73], s[8:9], 0, v[172:173]
	s_add_i32 m0, s41, 0xc000
	ds_read_b128 v[206:209], v199
	ds_read_b128 v[210:213], v199 offset:1024
	ds_read_b128 v[214:217], v199 offset:2048
	ds_read_b128 v[226:229], v199 offset:3072
	ds_read_b128 v[230:233], v199 offset:4096
	ds_read_b128 v[234:237], v199 offset:5120
	ds_read_b128 v[238:241], v199 offset:6144
	ds_read_b128 v[242:245], v199 offset:7168
	global_load_lds_dwordx4 v[72:73], off
	v_lshl_add_u64 v[72:73], s[8:9], 0, v[170:171]
	s_add_i32 m0, s41, 0xe000
	s_nop 0
	global_load_lds_dwordx4 v[72:73], off
	s_waitcnt vmcnt(8)
	s_waitcnt lgkmcnt(0)
	s_barrier
	s_setprio 1
	v_mfma_f32_16x16x32_bf16 v[142:145], v[68:71], v[206:209], v[142:145]
	v_mfma_f32_16x16x32_bf16 v[138:141], v[86:89], v[206:209], v[138:141]
	v_mfma_f32_16x16x32_bf16 v[126:129], v[68:71], v[214:217], v[126:129]
	v_mfma_f32_16x16x32_bf16 v[122:125], v[86:89], v[214:217], v[122:125]
	v_mfma_f32_16x16x32_bf16 v[110:113], v[68:71], v[230:233], v[110:113]
	v_mfma_f32_16x16x32_bf16 v[106:109], v[86:89], v[230:233], v[106:109]
	v_mfma_f32_16x16x32_bf16 v[94:97], v[68:71], v[238:241], v[94:97]
	v_mfma_f32_16x16x32_bf16 v[90:93], v[86:89], v[238:241], v[90:93]
	v_mfma_f32_16x16x32_bf16 v[142:145], v[82:85], v[210:213], v[142:145]
	v_mfma_f32_16x16x32_bf16 v[138:141], v[146:149], v[210:213], v[138:141]
	v_mfma_f32_16x16x32_bf16 v[126:129], v[82:85], v[226:229], v[126:129]
	v_mfma_f32_16x16x32_bf16 v[122:125], v[146:149], v[226:229], v[122:125]
	v_mfma_f32_16x16x32_bf16 v[110:113], v[82:85], v[234:237], v[110:113]
	v_mfma_f32_16x16x32_bf16 v[106:109], v[146:149], v[234:237], v[106:109]
	v_mfma_f32_16x16x32_bf16 v[94:97], v[82:85], v[242:245], v[94:97]
	v_mfma_f32_16x16x32_bf16 v[90:93], v[146:149], v[242:245], v[90:93]
	v_mfma_f32_16x16x32_bf16 v[134:137], v[150:153], v[206:209], v[134:137]
	v_mfma_f32_16x16x32_bf16 v[130:133], v[158:161], v[206:209], v[130:133]
	v_mfma_f32_16x16x32_bf16 v[118:121], v[150:153], v[214:217], v[118:121]
	v_mfma_f32_16x16x32_bf16 v[114:117], v[158:161], v[214:217], v[114:117]
	v_mfma_f32_16x16x32_bf16 v[102:105], v[150:153], v[230:233], v[102:105]
	v_mfma_f32_16x16x32_bf16 v[98:101], v[158:161], v[230:233], v[98:101]
	v_mfma_f32_16x16x32_bf16 v[78:81], v[150:153], v[238:241], v[78:81]
	v_mfma_f32_16x16x32_bf16 v[72:75], v[158:161], v[238:241], v[74:77]
	v_mfma_f32_16x16x32_bf16 v[134:137], v[154:157], v[210:213], v[134:137]
	v_mfma_f32_16x16x32_bf16 v[130:133], v[202:205], v[210:213], v[130:133]
	v_mfma_f32_16x16x32_bf16 v[118:121], v[154:157], v[226:229], v[118:121]
	v_mfma_f32_16x16x32_bf16 v[114:117], v[202:205], v[226:229], v[114:117]
	v_mfma_f32_16x16x32_bf16 v[102:105], v[154:157], v[234:237], v[102:105]
	v_mfma_f32_16x16x32_bf16 v[98:101], v[202:205], v[234:237], v[98:101]
	v_mfma_f32_16x16x32_bf16 v[78:81], v[154:157], v[242:245], v[78:81]
	v_mfma_f32_16x16x32_bf16 v[72:75], v[202:205], v[242:245], v[72:75]
	s_setprio 0
	s_barrier
	s_add_i32 s57, s57, s40
	v_lshl_add_u64 v[178:179], s[30:31], 0, v[0:1]
	s_mov_b32 m0, s57
	ds_read_b128 v[206:209], v199 offset:16384
	ds_read_b128 v[210:213], v199 offset:17408
	ds_read_b128 v[214:217], v199 offset:18432
	ds_read_b128 v[226:229], v199 offset:19456
	ds_read_b128 v[230:233], v199 offset:20480
	ds_read_b128 v[234:237], v199 offset:21504
	ds_read_b128 v[238:241], v199 offset:22528
	ds_read_b128 v[242:245], v199 offset:23552
	global_load_lds_dwordx4 v[178:179], off
	s_add_i32 m0, s57, 0x2000
	s_add_u32 s60, s30, 0x80000
	v_lshl_add_u64 v[250:251], s[30:31], 0, v[162:163]
	s_addc_u32 s61, s31, 0
	s_add_i32 s57, s62, s40
	global_load_lds_dwordx4 v[250:251], off
	v_lshl_add_u64 v[76:77], s[60:61], 0, v[0:1]
	s_mov_b32 m0, s57
	v_lshl_add_u64 v[252:253], s[34:35], 0, v[166:167]
	global_load_lds_dwordx4 v[76:77], off
	v_lshl_add_u64 v[76:77], s[60:61], 0, v[162:163]
	s_add_i32 m0, s57, 0x2000
	v_lshl_add_u64 v[220:221], s[34:35], 0, v[164:165]
	global_load_lds_dwordx4 v[76:77], off
	s_mov_b32 m0, s41
	s_nop 0
	global_load_lds_dwordx4 v[252:253], off
	s_mov_b32 m0, s42
	s_nop 0
	global_load_lds_dwordx4 v[220:221], off
	s_waitcnt vmcnt(8)
	s_waitcnt lgkmcnt(0)
	s_barrier
	s_setprio 1
	v_mfma_f32_16x16x32_bf16 v[62:65], v[68:71], v[206:209], v[62:65]
	v_mfma_f32_16x16x32_bf16 v[58:61], v[86:89], v[206:209], v[58:61]
	v_mfma_f32_16x16x32_bf16 v[46:49], v[68:71], v[214:217], v[46:49]
	v_mfma_f32_16x16x32_bf16 v[42:45], v[86:89], v[214:217], v[42:45]
	v_mfma_f32_16x16x32_bf16 v[30:33], v[68:71], v[230:233], v[30:33]
	v_mfma_f32_16x16x32_bf16 v[26:29], v[86:89], v[230:233], v[26:29]
	v_mfma_f32_16x16x32_bf16 v[14:17], v[68:71], v[238:241], v[14:17]
	v_mfma_f32_16x16x32_bf16 v[10:13], v[86:89], v[238:241], v[10:13]
	v_mfma_f32_16x16x32_bf16 v[62:65], v[82:85], v[210:213], v[62:65]
	v_mfma_f32_16x16x32_bf16 v[58:61], v[146:149], v[210:213], v[58:61]
	v_mfma_f32_16x16x32_bf16 v[46:49], v[82:85], v[226:229], v[46:49]
	v_mfma_f32_16x16x32_bf16 v[42:45], v[146:149], v[226:229], v[42:45]
	v_mfma_f32_16x16x32_bf16 v[30:33], v[82:85], v[234:237], v[30:33]
	v_mfma_f32_16x16x32_bf16 v[26:29], v[146:149], v[234:237], v[26:29]
	v_mfma_f32_16x16x32_bf16 v[14:17], v[82:85], v[242:245], v[14:17]
	v_mfma_f32_16x16x32_bf16 v[10:13], v[146:149], v[242:245], v[10:13]
	v_mfma_f32_16x16x32_bf16 v[54:57], v[150:153], v[206:209], v[54:57]
	v_mfma_f32_16x16x32_bf16 v[50:53], v[158:161], v[206:209], v[50:53]
	v_mfma_f32_16x16x32_bf16 v[38:41], v[150:153], v[214:217], v[38:41]
	v_mfma_f32_16x16x32_bf16 v[34:37], v[158:161], v[214:217], v[34:37]
	v_mfma_f32_16x16x32_bf16 v[22:25], v[150:153], v[230:233], v[22:25]
	v_mfma_f32_16x16x32_bf16 v[18:21], v[158:161], v[230:233], v[18:21]
	v_mfma_f32_16x16x32_bf16 v[6:9], v[150:153], v[238:241], v[6:9]
	v_mfma_f32_16x16x32_bf16 v[2:5], v[158:161], v[238:241], v[2:5]
	v_mfma_f32_16x16x32_bf16 v[54:57], v[154:157], v[210:213], v[54:57]
	v_mfma_f32_16x16x32_bf16 v[50:53], v[202:205], v[210:213], v[50:53]
	v_mfma_f32_16x16x32_bf16 v[38:41], v[154:157], v[226:229], v[38:41]
	v_mfma_f32_16x16x32_bf16 v[34:37], v[202:205], v[226:229], v[34:37]
	v_mfma_f32_16x16x32_bf16 v[22:25], v[154:157], v[234:237], v[22:25]
	v_mfma_f32_16x16x32_bf16 v[18:21], v[202:205], v[234:237], v[18:21]
	v_mfma_f32_16x16x32_bf16 v[6:9], v[154:157], v[242:245], v[6:9]
	v_mfma_f32_16x16x32_bf16 v[2:5], v[202:205], v[242:245], v[2:5]
	s_setprio 0
	s_barrier
	s_add_i32 s57, 0, 0x18000
	v_add_u32_e32 v76, s57, v181
	s_add_i32 s60, 0, 0x1c000
	ds_read_b128 v[68:71], v76
	ds_read_b128 v[82:85], v76 offset:1024
	ds_read_b128 v[86:89], v76 offset:2048
	ds_read_b128 v[146:149], v76 offset:3072
	v_add_u32_e32 v76, s60, v181
	ds_read_b128 v[150:153], v76
	ds_read_b128 v[154:157], v76 offset:1024
	ds_read_b128 v[158:161], v76 offset:2048
	ds_read_b128 v[202:205], v76 offset:3072
	s_add_u32 s34, s34, 0x80000
	s_addc_u32 s35, s35, 0
	s_mov_b32 m0, s43
	v_lshl_add_u64 v[76:77], s[34:35], 0, v[166:167]
	ds_read_b128 v[206:209], v199 offset:32768
	ds_read_b128 v[210:213], v199 offset:33792
	ds_read_b128 v[214:217], v199 offset:34816
	ds_read_b128 v[226:229], v199 offset:35840
	ds_read_b128 v[230:233], v199 offset:36864
	ds_read_b128 v[234:237], v199 offset:37888
	ds_read_b128 v[238:241], v199 offset:38912
	ds_read_b128 v[242:245], v199 offset:39936
	global_load_lds_dwordx4 v[76:77], off
	v_lshl_add_u64 v[76:77], s[34:35], 0, v[164:165]
	s_mov_b32 m0, s44
	s_nop 0
	global_load_lds_dwordx4 v[76:77], off
	s_waitcnt vmcnt(8)
	s_waitcnt lgkmcnt(0)
	s_barrier
	s_setprio 1
	v_mfma_f32_16x16x32_bf16 v[142:145], v[68:71], v[206:209], v[142:145]
	v_mfma_f32_16x16x32_bf16 v[138:141], v[86:89], v[206:209], v[138:141]
	v_mfma_f32_16x16x32_bf16 v[126:129], v[68:71], v[214:217], v[126:129]
	v_mfma_f32_16x16x32_bf16 v[122:125], v[86:89], v[214:217], v[122:125]
	v_mfma_f32_16x16x32_bf16 v[110:113], v[68:71], v[230:233], v[110:113]
	v_mfma_f32_16x16x32_bf16 v[106:109], v[86:89], v[230:233], v[106:109]
	v_mfma_f32_16x16x32_bf16 v[94:97], v[68:71], v[238:241], v[94:97]
	v_mfma_f32_16x16x32_bf16 v[90:93], v[86:89], v[238:241], v[90:93]
	v_mfma_f32_16x16x32_bf16 v[142:145], v[82:85], v[210:213], v[142:145]
	v_mfma_f32_16x16x32_bf16 v[138:141], v[146:149], v[210:213], v[138:141]
	v_mfma_f32_16x16x32_bf16 v[126:129], v[82:85], v[226:229], v[126:129]
	v_mfma_f32_16x16x32_bf16 v[122:125], v[146:149], v[226:229], v[122:125]
	v_mfma_f32_16x16x32_bf16 v[110:113], v[82:85], v[234:237], v[110:113]
	v_mfma_f32_16x16x32_bf16 v[106:109], v[146:149], v[234:237], v[106:109]
	v_mfma_f32_16x16x32_bf16 v[94:97], v[82:85], v[242:245], v[94:97]
	v_mfma_f32_16x16x32_bf16 v[90:93], v[146:149], v[242:245], v[90:93]
	v_mfma_f32_16x16x32_bf16 v[134:137], v[150:153], v[206:209], v[134:137]
	v_mfma_f32_16x16x32_bf16 v[130:133], v[158:161], v[206:209], v[130:133]
	v_mfma_f32_16x16x32_bf16 v[118:121], v[150:153], v[214:217], v[118:121]
	v_mfma_f32_16x16x32_bf16 v[114:117], v[158:161], v[214:217], v[114:117]
	v_mfma_f32_16x16x32_bf16 v[102:105], v[150:153], v[230:233], v[102:105]
	v_mfma_f32_16x16x32_bf16 v[98:101], v[158:161], v[230:233], v[98:101]
	v_mfma_f32_16x16x32_bf16 v[76:79], v[150:153], v[238:241], v[78:81]
	v_mfma_f32_16x16x32_bf16 v[72:75], v[158:161], v[238:241], v[72:75]
	v_mfma_f32_16x16x32_bf16 v[134:137], v[154:157], v[210:213], v[134:137]
	v_mfma_f32_16x16x32_bf16 v[130:133], v[202:205], v[210:213], v[130:133]
	v_mfma_f32_16x16x32_bf16 v[118:121], v[154:157], v[226:229], v[118:121]
	v_mfma_f32_16x16x32_bf16 v[114:117], v[202:205], v[226:229], v[114:117]
	v_mfma_f32_16x16x32_bf16 v[102:105], v[154:157], v[234:237], v[102:105]
	v_mfma_f32_16x16x32_bf16 v[98:101], v[202:205], v[234:237], v[98:101]
	v_mfma_f32_16x16x32_bf16 v[78:81], v[154:157], v[242:245], v[76:79]
	v_mfma_f32_16x16x32_bf16 v[74:77], v[202:205], v[242:245], v[72:75]
	s_setprio 0
	s_barrier
	s_add_i32 s34, s57, s40
	v_lshl_add_u64 v[72:73], v[178:179], 0, s[96:97]
	s_mov_b32 m0, s34
	ds_read_b128 v[206:209], v199 offset:49152
	ds_read_b128 v[210:213], v199 offset:50176
	ds_read_b128 v[214:217], v199 offset:51200
	ds_read_b128 v[226:229], v199 offset:52224
	ds_read_b128 v[230:233], v199 offset:53248
	ds_read_b128 v[234:237], v199 offset:54272
	ds_read_b128 v[238:241], v199 offset:55296
	ds_read_b128 v[242:245], v199 offset:56320
	global_load_lds_dwordx4 v[72:73], off
	s_add_i32 m0, s34, 0x2000
	s_add_u32 s30, s30, 0x80080
	v_lshl_add_u64 v[72:73], v[250:251], 0, s[96:97]
	s_addc_u32 s31, s31, 0
	s_add_i32 s34, s60, s40
	global_load_lds_dwordx4 v[72:73], off
	v_lshl_add_u64 v[72:73], s[30:31], 0, v[0:1]
	s_mov_b32 m0, s34
	s_nop 0
	global_load_lds_dwordx4 v[72:73], off
	v_lshl_add_u64 v[72:73], s[30:31], 0, v[162:163]
	s_add_i32 m0, s34, 0x2000
	s_nop 0
	global_load_lds_dwordx4 v[72:73], off
	v_lshl_add_u64 v[72:73], v[252:253], 0, s[96:97]
	s_mov_b32 m0, s47
	s_nop 0
	global_load_lds_dwordx4 v[72:73], off
	v_lshl_add_u64 v[72:73], v[220:221], 0, s[96:97]
	s_mov_b32 m0, s50
	s_nop 0
	global_load_lds_dwordx4 v[72:73], off
	s_waitcnt vmcnt(8)
	s_waitcnt lgkmcnt(0)
	s_barrier
	s_setprio 1
	v_mfma_f32_16x16x32_bf16 v[62:65], v[68:71], v[206:209], v[62:65]
	v_mfma_f32_16x16x32_bf16 v[58:61], v[86:89], v[206:209], v[58:61]
	v_mfma_f32_16x16x32_bf16 v[46:49], v[68:71], v[214:217], v[46:49]
	v_mfma_f32_16x16x32_bf16 v[42:45], v[86:89], v[214:217], v[42:45]
	v_mfma_f32_16x16x32_bf16 v[30:33], v[68:71], v[230:233], v[30:33]
	v_mfma_f32_16x16x32_bf16 v[26:29], v[86:89], v[230:233], v[26:29]
	v_mfma_f32_16x16x32_bf16 v[14:17], v[68:71], v[238:241], v[14:17]
	v_mfma_f32_16x16x32_bf16 v[10:13], v[86:89], v[238:241], v[10:13]
	v_mfma_f32_16x16x32_bf16 v[62:65], v[82:85], v[210:213], v[62:65]
	v_mfma_f32_16x16x32_bf16 v[58:61], v[146:149], v[210:213], v[58:61]
	v_mfma_f32_16x16x32_bf16 v[46:49], v[82:85], v[226:229], v[46:49]
	v_mfma_f32_16x16x32_bf16 v[42:45], v[146:149], v[226:229], v[42:45]
	v_mfma_f32_16x16x32_bf16 v[30:33], v[82:85], v[234:237], v[30:33]
	v_mfma_f32_16x16x32_bf16 v[26:29], v[146:149], v[234:237], v[26:29]
	v_mfma_f32_16x16x32_bf16 v[14:17], v[82:85], v[242:245], v[14:17]
	v_mfma_f32_16x16x32_bf16 v[10:13], v[146:149], v[242:245], v[10:13]
	v_mfma_f32_16x16x32_bf16 v[54:57], v[150:153], v[206:209], v[54:57]
	v_mfma_f32_16x16x32_bf16 v[50:53], v[158:161], v[206:209], v[50:53]
	v_mfma_f32_16x16x32_bf16 v[38:41], v[150:153], v[214:217], v[38:41]
	v_mfma_f32_16x16x32_bf16 v[34:37], v[158:161], v[214:217], v[34:37]
	v_mfma_f32_16x16x32_bf16 v[22:25], v[150:153], v[230:233], v[22:25]
	v_mfma_f32_16x16x32_bf16 v[18:21], v[158:161], v[230:233], v[18:21]
	v_mfma_f32_16x16x32_bf16 v[6:9], v[150:153], v[238:241], v[6:9]
	v_mfma_f32_16x16x32_bf16 v[2:5], v[158:161], v[238:241], v[2:5]
	v_mfma_f32_16x16x32_bf16 v[54:57], v[154:157], v[210:213], v[54:57]
	v_mfma_f32_16x16x32_bf16 v[50:53], v[202:205], v[210:213], v[50:53]
	v_mfma_f32_16x16x32_bf16 v[38:41], v[154:157], v[226:229], v[38:41]
	v_mfma_f32_16x16x32_bf16 v[34:37], v[202:205], v[226:229], v[34:37]
	v_mfma_f32_16x16x32_bf16 v[22:25], v[154:157], v[234:237], v[22:25]
	v_mfma_f32_16x16x32_bf16 v[18:21], v[202:205], v[234:237], v[18:21]
	v_mfma_f32_16x16x32_bf16 v[6:9], v[154:157], v[242:245], v[6:9]
	v_mfma_f32_16x16x32_bf16 v[2:5], v[202:205], v[242:245], v[2:5]
	s_setprio 0
	s_barrier
	s_add_i32 s56, s56, 2
	s_add_u32 s1, s1, 0x100
	s_addc_u32 s55, s55, 0
	s_add_u32 s8, s8, 0x100
	s_addc_u32 s9, s9, 0
	s_cmp_gt_u32 s56, 29
	s_cbranch_scc1 .LBB0_273

.LBB0_617:
	s_add_u32 s34, s8, 0xfff80080
	s_addc_u32 s35, s9, -1
	s_add_i32 s64, 0, 0x10000
	s_cmp_eq_u32 s63, 28
	s_cselect_b32 s37, s21, s35
	s_cselect_b32 s36, s23, s34
	v_add_u32_e32 v0, s64, v212
	s_cselect_b32 s35, s25, s62
	s_cselect_b32 s34, s27, s61
	s_add_i32 s66, 0, 0x14000
	ds_read_b128 v[66:69], v0
	ds_read_b128 v[70:73], v0 offset:1024
	ds_read_b128 v[74:77], v0 offset:2048
	ds_read_b128 v[78:81], v0 offset:3072
	v_add_u32_e32 v0, s66, v212
	ds_read_b128 v[130:133], v0
	ds_read_b128 v[142:145], v0 offset:1024
	ds_read_b128 v[146:149], v0 offset:2048
	ds_read_b128 v[158:161], v0 offset:3072
	v_lshl_add_u64 v[220:221], s[8:9], 0, v[190:191]
	s_add_i32 m0, s42, 0xc000
	ds_read_b128 v[162:165], v215
	ds_read_b128 v[166:169], v215 offset:1024
	ds_read_b128 v[170:173], v215 offset:2048
	ds_read_b128 v[192:195], v215 offset:3072
	ds_read_b128 v[196:199], v215 offset:4096
	ds_read_b128 v[200:203], v215 offset:5120
	ds_read_b128 v[204:207], v215 offset:6144
	ds_read_b128 v[208:211], v215 offset:7168
	global_load_lds_dwordx4 v[220:221], off
	v_lshl_add_u64 v[220:221], s[8:9], 0, v[188:189]
	s_add_i32 m0, s42, 0xe000
	s_nop 0
	global_load_lds_dwordx4 v[220:221], off
	s_waitcnt vmcnt(8)
	s_waitcnt lgkmcnt(0)
	s_barrier
	s_setprio 1
	v_mfma_f32_16x16x32_bf16 v[154:157], v[66:69], v[162:165], v[154:157]
	v_mfma_f32_16x16x32_bf16 v[150:153], v[74:77], v[162:165], v[150:153]
	v_mfma_f32_16x16x32_bf16 v[138:141], v[66:69], v[170:173], v[138:141]
	v_mfma_f32_16x16x32_bf16 v[134:137], v[74:77], v[170:173], v[134:137]
	v_mfma_f32_16x16x32_bf16 v[110:113], v[66:69], v[196:199], v[110:113]
	v_mfma_f32_16x16x32_bf16 v[106:109], v[74:77], v[196:199], v[106:109]
	v_mfma_f32_16x16x32_bf16 v[94:97], v[66:69], v[204:207], v[94:97]
	v_mfma_f32_16x16x32_bf16 v[90:93], v[74:77], v[204:207], v[90:93]
	v_mfma_f32_16x16x32_bf16 v[154:157], v[70:73], v[166:169], v[154:157]
	v_mfma_f32_16x16x32_bf16 v[150:153], v[78:81], v[166:169], v[150:153]
	v_mfma_f32_16x16x32_bf16 v[138:141], v[70:73], v[192:195], v[138:141]
	v_mfma_f32_16x16x32_bf16 v[134:137], v[78:81], v[192:195], v[134:137]
	v_mfma_f32_16x16x32_bf16 v[110:113], v[70:73], v[200:203], v[110:113]
	v_mfma_f32_16x16x32_bf16 v[106:109], v[78:81], v[200:203], v[106:109]
	v_mfma_f32_16x16x32_bf16 v[94:97], v[70:73], v[208:211], v[94:97]
	v_mfma_f32_16x16x32_bf16 v[90:93], v[78:81], v[208:211], v[90:93]
	v_mfma_f32_16x16x32_bf16 v[126:129], v[130:133], v[162:165], v[126:129]
	v_mfma_f32_16x16x32_bf16 v[114:117], v[146:149], v[162:165], v[114:117]
	v_mfma_f32_16x16x32_bf16 v[122:125], v[130:133], v[170:173], v[122:125]
	v_mfma_f32_16x16x32_bf16 v[118:121], v[146:149], v[170:173], v[118:121]
	v_mfma_f32_16x16x32_bf16 v[102:105], v[130:133], v[196:199], v[102:105]
	v_mfma_f32_16x16x32_bf16 v[98:101], v[146:149], v[196:199], v[98:101]
	v_mfma_f32_16x16x32_bf16 v[86:89], v[130:133], v[204:207], v[86:89]
	v_mfma_f32_16x16x32_bf16 v[82:85], v[146:149], v[204:207], v[82:85]
	v_mfma_f32_16x16x32_bf16 v[126:129], v[142:145], v[166:169], v[126:129]
	v_mfma_f32_16x16x32_bf16 v[114:117], v[158:161], v[166:169], v[114:117]
	v_mfma_f32_16x16x32_bf16 v[122:125], v[142:145], v[192:195], v[122:125]
	v_mfma_f32_16x16x32_bf16 v[118:121], v[158:161], v[192:195], v[118:121]
	v_mfma_f32_16x16x32_bf16 v[102:105], v[142:145], v[200:203], v[102:105]
	v_mfma_f32_16x16x32_bf16 v[98:101], v[158:161], v[200:203], v[98:101]
	v_mfma_f32_16x16x32_bf16 v[86:89], v[142:145], v[208:211], v[86:89]
	v_mfma_f32_16x16x32_bf16 v[82:85], v[158:161], v[208:211], v[82:85]
	s_setprio 0
	s_barrier
	s_add_i32 s64, s64, s41
	v_lshl_add_u64 v[220:221], s[34:35], 0, v[182:183]
	s_mov_b32 m0, s64
	ds_read_b128 v[162:165], v215 offset:16384
	ds_read_b128 v[166:169], v215 offset:17408
	ds_read_b128 v[170:173], v215 offset:18432
	ds_read_b128 v[192:195], v215 offset:19456
	ds_read_b128 v[196:199], v215 offset:20480
	ds_read_b128 v[200:203], v215 offset:21504
	ds_read_b128 v[204:207], v215 offset:22528
	ds_read_b128 v[208:211], v215 offset:23552
	global_load_lds_dwordx4 v[220:221], off
	s_add_i32 m0, s64, 0x2000
	s_add_u32 s64, s34, 0x80000
	v_lshl_add_u64 v[230:231], s[34:35], 0, v[178:179]
	s_addc_u32 s65, s35, 0
	s_add_i32 s66, s66, s41
	global_load_lds_dwordx4 v[230:231], off
	v_lshl_add_u64 v[232:233], s[64:65], 0, v[182:183]
	s_mov_b32 m0, s66
	v_lshl_add_u64 v[234:235], s[36:37], 0, v[180:181]
	global_load_lds_dwordx4 v[232:233], off
	v_lshl_add_u64 v[232:233], s[64:65], 0, v[178:179]
	s_add_i32 m0, s66, 0x2000
	s_nop 0
	global_load_lds_dwordx4 v[232:233], off
	v_lshl_add_u64 v[232:233], s[36:37], 0, v[184:185]
	s_mov_b32 m0, s42
	s_nop 0
	global_load_lds_dwordx4 v[232:233], off
	s_mov_b32 m0, s43
	s_nop 0
	global_load_lds_dwordx4 v[234:235], off
	s_waitcnt vmcnt(8)
	s_waitcnt lgkmcnt(0)
	s_barrier
	s_setprio 1
	v_mfma_f32_16x16x32_bf16 v[62:65], v[66:69], v[162:165], v[62:65]
	v_mfma_f32_16x16x32_bf16 v[58:61], v[74:77], v[162:165], v[58:61]
	v_mfma_f32_16x16x32_bf16 v[46:49], v[66:69], v[170:173], v[46:49]
	v_mfma_f32_16x16x32_bf16 v[42:45], v[74:77], v[170:173], v[42:45]
	v_mfma_f32_16x16x32_bf16 v[30:33], v[66:69], v[196:199], v[30:33]
	v_mfma_f32_16x16x32_bf16 v[26:29], v[74:77], v[196:199], v[26:29]
	v_mfma_f32_16x16x32_bf16 v[14:17], v[66:69], v[204:207], v[14:17]
	v_mfma_f32_16x16x32_bf16 v[10:13], v[74:77], v[204:207], v[10:13]
	v_mfma_f32_16x16x32_bf16 v[62:65], v[70:73], v[166:169], v[62:65]
	v_mfma_f32_16x16x32_bf16 v[58:61], v[78:81], v[166:169], v[58:61]
	v_mfma_f32_16x16x32_bf16 v[46:49], v[70:73], v[192:195], v[46:49]
	v_mfma_f32_16x16x32_bf16 v[42:45], v[78:81], v[192:195], v[42:45]
	v_mfma_f32_16x16x32_bf16 v[30:33], v[70:73], v[200:203], v[30:33]
	v_mfma_f32_16x16x32_bf16 v[26:29], v[78:81], v[200:203], v[26:29]
	v_mfma_f32_16x16x32_bf16 v[14:17], v[70:73], v[208:211], v[14:17]
	v_mfma_f32_16x16x32_bf16 v[10:13], v[78:81], v[208:211], v[10:13]
	v_mfma_f32_16x16x32_bf16 v[54:57], v[130:133], v[162:165], v[54:57]
	v_mfma_f32_16x16x32_bf16 v[50:53], v[146:149], v[162:165], v[50:53]
	v_mfma_f32_16x16x32_bf16 v[38:41], v[130:133], v[170:173], v[38:41]
	v_mfma_f32_16x16x32_bf16 v[34:37], v[146:149], v[170:173], v[34:37]
	v_mfma_f32_16x16x32_bf16 v[22:25], v[130:133], v[196:199], v[22:25]
	v_mfma_f32_16x16x32_bf16 v[18:21], v[146:149], v[196:199], v[18:21]
	v_mfma_f32_16x16x32_bf16 v[6:9], v[130:133], v[204:207], v[6:9]
	v_mfma_f32_16x16x32_bf16 v[2:5], v[146:149], v[204:207], v[2:5]
	v_mfma_f32_16x16x32_bf16 v[54:57], v[142:145], v[166:169], v[54:57]
	v_mfma_f32_16x16x32_bf16 v[50:53], v[158:161], v[166:169], v[50:53]
	v_mfma_f32_16x16x32_bf16 v[38:41], v[142:145], v[192:195], v[38:41]
	v_mfma_f32_16x16x32_bf16 v[34:37], v[158:161], v[192:195], v[34:37]
	v_mfma_f32_16x16x32_bf16 v[22:25], v[142:145], v[200:203], v[22:25]
	v_mfma_f32_16x16x32_bf16 v[18:21], v[158:161], v[200:203], v[18:21]
	v_mfma_f32_16x16x32_bf16 v[6:9], v[142:145], v[208:211], v[6:9]
	v_mfma_f32_16x16x32_bf16 v[2:5], v[158:161], v[208:211], v[2:5]
	s_setprio 0
	s_barrier
	s_add_i32 s64, 0, 0x18000
	v_add_u32_e32 v0, s64, v212
	s_add_i32 s65, 0, 0x1c000
	ds_read_b128 v[66:69], v0
	ds_read_b128 v[70:73], v0 offset:1024
	ds_read_b128 v[74:77], v0 offset:2048
	ds_read_b128 v[78:81], v0 offset:3072
	v_add_u32_e32 v0, s65, v212
	ds_read_b128 v[130:133], v0
	ds_read_b128 v[142:145], v0 offset:1024
	ds_read_b128 v[146:149], v0 offset:2048
	ds_read_b128 v[158:161], v0 offset:3072
	s_add_u32 s36, s36, 0x80000
	s_addc_u32 s37, s37, 0
	s_mov_b32 m0, s44
	v_lshl_add_u64 v[236:237], s[36:37], 0, v[184:185]
	ds_read_b128 v[162:165], v215 offset:32768
	ds_read_b128 v[166:169], v215 offset:33792
	ds_read_b128 v[170:173], v215 offset:34816
	ds_read_b128 v[192:195], v215 offset:35840
	ds_read_b128 v[196:199], v215 offset:36864
	ds_read_b128 v[200:203], v215 offset:37888
	ds_read_b128 v[204:207], v215 offset:38912
	ds_read_b128 v[208:211], v215 offset:39936
	global_load_lds_dwordx4 v[236:237], off
	v_lshl_add_u64 v[236:237], s[36:37], 0, v[180:181]
	s_mov_b32 m0, s45
	s_nop 0
	global_load_lds_dwordx4 v[236:237], off
	s_waitcnt vmcnt(8)
	s_waitcnt lgkmcnt(0)
	s_barrier
	s_setprio 1
	v_mfma_f32_16x16x32_bf16 v[154:157], v[66:69], v[162:165], v[154:157]
	v_mfma_f32_16x16x32_bf16 v[150:153], v[74:77], v[162:165], v[150:153]
	v_mfma_f32_16x16x32_bf16 v[138:141], v[66:69], v[170:173], v[138:141]
	v_mfma_f32_16x16x32_bf16 v[134:137], v[74:77], v[170:173], v[134:137]
	v_mfma_f32_16x16x32_bf16 v[110:113], v[66:69], v[196:199], v[110:113]
	v_mfma_f32_16x16x32_bf16 v[106:109], v[74:77], v[196:199], v[106:109]
	v_mfma_f32_16x16x32_bf16 v[94:97], v[66:69], v[204:207], v[94:97]
	v_mfma_f32_16x16x32_bf16 v[90:93], v[74:77], v[204:207], v[90:93]
	v_mfma_f32_16x16x32_bf16 v[154:157], v[70:73], v[166:169], v[154:157]
	v_mfma_f32_16x16x32_bf16 v[150:153], v[78:81], v[166:169], v[150:153]
	v_mfma_f32_16x16x32_bf16 v[138:141], v[70:73], v[192:195], v[138:141]
	v_mfma_f32_16x16x32_bf16 v[134:137], v[78:81], v[192:195], v[134:137]
	v_mfma_f32_16x16x32_bf16 v[110:113], v[70:73], v[200:203], v[110:113]
	v_mfma_f32_16x16x32_bf16 v[106:109], v[78:81], v[200:203], v[106:109]
	v_mfma_f32_16x16x32_bf16 v[94:97], v[70:73], v[208:211], v[94:97]
	v_mfma_f32_16x16x32_bf16 v[90:93], v[78:81], v[208:211], v[90:93]
	v_mfma_f32_16x16x32_bf16 v[126:129], v[130:133], v[162:165], v[126:129]
	v_mfma_f32_16x16x32_bf16 v[114:117], v[146:149], v[162:165], v[114:117]
	v_mfma_f32_16x16x32_bf16 v[122:125], v[130:133], v[170:173], v[122:125]
	v_mfma_f32_16x16x32_bf16 v[118:121], v[146:149], v[170:173], v[118:121]
	v_mfma_f32_16x16x32_bf16 v[102:105], v[130:133], v[196:199], v[102:105]
	v_mfma_f32_16x16x32_bf16 v[98:101], v[146:149], v[196:199], v[98:101]
	v_mfma_f32_16x16x32_bf16 v[86:89], v[130:133], v[204:207], v[86:89]
	v_mfma_f32_16x16x32_bf16 v[82:85], v[146:149], v[204:207], v[82:85]
	v_mfma_f32_16x16x32_bf16 v[126:129], v[142:145], v[166:169], v[126:129]
	v_mfma_f32_16x16x32_bf16 v[114:117], v[158:161], v[166:169], v[114:117]
	v_mfma_f32_16x16x32_bf16 v[122:125], v[142:145], v[192:195], v[122:125]
	v_mfma_f32_16x16x32_bf16 v[118:121], v[158:161], v[192:195], v[118:121]
	v_mfma_f32_16x16x32_bf16 v[102:105], v[142:145], v[200:203], v[102:105]
	v_mfma_f32_16x16x32_bf16 v[98:101], v[158:161], v[200:203], v[98:101]
	v_mfma_f32_16x16x32_bf16 v[86:89], v[142:145], v[208:211], v[86:89]
	v_mfma_f32_16x16x32_bf16 v[82:85], v[158:161], v[208:211], v[82:85]
	s_setprio 0
	s_barrier
	s_add_i32 s36, s64, s41
	v_lshl_add_u64 v[220:221], v[220:221], 0, s[96:97]
	s_mov_b32 m0, s36
	ds_read_b128 v[162:165], v215 offset:49152
	ds_read_b128 v[166:169], v215 offset:50176
	ds_read_b128 v[170:173], v215 offset:51200
	ds_read_b128 v[192:195], v215 offset:52224
	ds_read_b128 v[196:199], v215 offset:53248
	ds_read_b128 v[200:203], v215 offset:54272
	ds_read_b128 v[204:207], v215 offset:55296
	ds_read_b128 v[208:211], v215 offset:56320
	global_load_lds_dwordx4 v[220:221], off
	s_add_i32 m0, s36, 0x2000
	s_add_u32 s34, s34, 0x80080
	v_lshl_add_u64 v[220:221], v[230:231], 0, s[96:97]
	s_addc_u32 s35, s35, 0
	s_add_i32 s36, s65, s41
	global_load_lds_dwordx4 v[220:221], off
	v_lshl_add_u64 v[220:221], s[34:35], 0, v[182:183]
	s_mov_b32 m0, s36
	s_nop 0
	global_load_lds_dwordx4 v[220:221], off
	v_lshl_add_u64 v[220:221], s[34:35], 0, v[178:179]
	s_add_i32 m0, s36, 0x2000
	s_nop 0
	global_load_lds_dwordx4 v[220:221], off
	v_lshl_add_u64 v[220:221], v[232:233], 0, s[96:97]
	s_mov_b32 m0, s56
	s_nop 0
	global_load_lds_dwordx4 v[220:221], off
	v_lshl_add_u64 v[220:221], v[234:235], 0, s[96:97]
	s_mov_b32 m0, s57
	s_nop 0
	global_load_lds_dwordx4 v[220:221], off
	s_waitcnt vmcnt(8)
	s_waitcnt lgkmcnt(0)
	s_barrier
	s_setprio 1
	v_mfma_f32_16x16x32_bf16 v[62:65], v[66:69], v[162:165], v[62:65]
	v_mfma_f32_16x16x32_bf16 v[58:61], v[74:77], v[162:165], v[58:61]
	v_mfma_f32_16x16x32_bf16 v[46:49], v[66:69], v[170:173], v[46:49]
	v_mfma_f32_16x16x32_bf16 v[42:45], v[74:77], v[170:173], v[42:45]
	v_mfma_f32_16x16x32_bf16 v[30:33], v[66:69], v[196:199], v[30:33]
	v_mfma_f32_16x16x32_bf16 v[26:29], v[74:77], v[196:199], v[26:29]
	v_mfma_f32_16x16x32_bf16 v[14:17], v[66:69], v[204:207], v[14:17]
	v_mfma_f32_16x16x32_bf16 v[10:13], v[74:77], v[204:207], v[10:13]
	v_mfma_f32_16x16x32_bf16 v[62:65], v[70:73], v[166:169], v[62:65]
	v_mfma_f32_16x16x32_bf16 v[58:61], v[78:81], v[166:169], v[58:61]
	v_mfma_f32_16x16x32_bf16 v[46:49], v[70:73], v[192:195], v[46:49]
	v_mfma_f32_16x16x32_bf16 v[42:45], v[78:81], v[192:195], v[42:45]
	v_mfma_f32_16x16x32_bf16 v[30:33], v[70:73], v[200:203], v[30:33]
	v_mfma_f32_16x16x32_bf16 v[26:29], v[78:81], v[200:203], v[26:29]
	v_mfma_f32_16x16x32_bf16 v[14:17], v[70:73], v[208:211], v[14:17]
	v_mfma_f32_16x16x32_bf16 v[10:13], v[78:81], v[208:211], v[10:13]
	v_mfma_f32_16x16x32_bf16 v[54:57], v[130:133], v[162:165], v[54:57]
	v_mfma_f32_16x16x32_bf16 v[50:53], v[146:149], v[162:165], v[50:53]
	v_mfma_f32_16x16x32_bf16 v[38:41], v[130:133], v[170:173], v[38:41]
	v_mfma_f32_16x16x32_bf16 v[34:37], v[146:149], v[170:173], v[34:37]
	v_mfma_f32_16x16x32_bf16 v[22:25], v[130:133], v[196:199], v[22:25]
	v_mfma_f32_16x16x32_bf16 v[18:21], v[146:149], v[196:199], v[18:21]
	v_mfma_f32_16x16x32_bf16 v[6:9], v[130:133], v[204:207], v[6:9]
	v_mfma_f32_16x16x32_bf16 v[2:5], v[146:149], v[204:207], v[2:5]
	v_mfma_f32_16x16x32_bf16 v[54:57], v[142:145], v[166:169], v[54:57]
	v_mfma_f32_16x16x32_bf16 v[50:53], v[158:161], v[166:169], v[50:53]
	v_mfma_f32_16x16x32_bf16 v[38:41], v[142:145], v[192:195], v[38:41]
	v_mfma_f32_16x16x32_bf16 v[34:37], v[158:161], v[192:195], v[34:37]
	v_mfma_f32_16x16x32_bf16 v[22:25], v[142:145], v[200:203], v[22:25]
	v_mfma_f32_16x16x32_bf16 v[18:21], v[158:161], v[200:203], v[18:21]
	v_mfma_f32_16x16x32_bf16 v[6:9], v[142:145], v[208:211], v[6:9]
	v_mfma_f32_16x16x32_bf16 v[2:5], v[158:161], v[208:211], v[2:5]
	s_setprio 0
	s_barrier
	s_add_i32 s63, s63, 2
	s_add_u32 s61, s61, 0x100
	s_addc_u32 s62, s62, 0
	s_add_u32 s8, s8, 0x100
	s_addc_u32 s9, s9, 0
	s_cmp_gt_u32 s63, 29
	s_cbranch_scc0 .LBB0_617
	s_and_b64 vcc, exec, s[14:15]
	s_cbranch_vccz .LBB0_620
	s_barrier
.LBB0_620:
	s_ashr_i32 s8, s22, 5
	v_lshl_or_b32 v130, s20, 8, v213
	s_mul_i32 s23, s8, 0xc000
	s_mul_hi_i32 s21, s8, 0xc000
	s_add_u32 s8, s52, s23
	v_ashrrev_i32_e32 v131, 31, v130
	s_addc_u32 s9, s53, s21
	v_lshlrev_b64 v[66:67], 2, v[130:131]
	v_lshl_add_u64 v[74:75], s[8:9], 0, v[66:67]
	global_load_dwordx4 v[70:73], v[74:75], off
	s_add_u32 s8, s54, s23
	s_addc_u32 s9, s55, s21
	v_cndmask_b32_e64 v0, 0, 1, s[18:19]
	v_lshl_add_u64 v[132:133], s[12:13], 0, v[66:67]
	v_lshl_add_u64 v[142:143], s[8:9], 0, v[66:67]
	v_mov_b32_e32 v198, 0
	v_cmp_ne_u32_e64 s[8:9], 1, v0
	s_andn2_b64 vcc, exec, s[18:19]
	v_mov_b32_e32 v200, 0
	v_mov_b32_e32 v201, 0
	v_mov_b32_e32 v204, 0
	v_mov_b32_e32 v205, 0
	s_cbranch_vccnz .LBB0_622
	global_load_dwordx4 v[66:69], v[142:143], off
	global_load_dwordx4 v[76:79], v[132:133], off
	s_waitcnt vmcnt(0)
	v_pk_add_f32 v[68:69], v[68:69], 1.0 op_sel_hi:[1,0]
	v_pk_add_f32 v[66:67], v[66:67], 1.0 op_sel_hi:[1,0]
	v_pk_mul_f32 v[204:205], v[78:79], v[68:69]
	v_pk_mul_f32 v[200:201], v[76:77], v[66:67]
.LBB0_622:
	global_load_dwordx4 v[78:81], v[74:75], off offset:16
	s_and_b64 vcc, exec, s[8:9]
	v_mov_b32_e32 v199, 0
	v_mov_b32_e32 v206, 0
	v_mov_b32_e32 v207, 0
	s_cbranch_vccnz .LBB0_624
	global_load_dwordx4 v[66:69], v[142:143], off offset:16
	global_load_dwordx4 v[144:147], v[132:133], off offset:16
	s_waitcnt vmcnt(0)
	v_pk_add_f32 v[68:69], v[68:69], 1.0 op_sel_hi:[1,0]
	v_pk_add_f32 v[66:67], v[66:67], 1.0 op_sel_hi:[1,0]
	v_pk_mul_f32 v[206:207], v[146:147], v[68:69]
	v_pk_mul_f32 v[198:199], v[144:145], v[66:67]
.LBB0_624:
	global_load_dwordx4 v[66:69], v[74:75], off offset:512
	v_mov_b32_e32 v192, 0
	s_and_b64 vcc, exec, s[8:9]
	v_mov_b32_e32 v194, 0
	v_mov_b32_e32 v195, 0
	v_mov_b32_e32 v196, 0
	v_mov_b32_e32 v197, 0
	s_cbranch_vccnz .LBB0_626
	global_load_dwordx4 v[144:147], v[142:143], off offset:512
	global_load_dwordx4 v[158:161], v[132:133], off offset:512
	s_waitcnt vmcnt(0)
	v_pk_add_f32 v[76:77], v[146:147], 1.0 op_sel_hi:[1,0]
	v_pk_add_f32 v[144:145], v[144:145], 1.0 op_sel_hi:[1,0]
	v_pk_mul_f32 v[196:197], v[160:161], v[76:77]
	v_pk_mul_f32 v[194:195], v[158:159], v[144:145]
.LBB0_626:
	global_load_dwordx4 v[74:77], v[74:75], off offset:528
	s_and_b64 vcc, exec, s[8:9]
	v_mov_b32_e32 v193, 0
	v_mov_b32_e32 v202, 0
	v_mov_b32_e32 v203, 0
	s_cbranch_vccnz .LBB0_628
	global_load_dwordx4 v[142:145], v[142:143], off offset:528
	s_nop 0
	global_load_dwordx4 v[146:149], v[132:133], off offset:528
	s_waitcnt vmcnt(0)
	v_pk_add_f32 v[132:133], v[144:145], 1.0 op_sel_hi:[1,0]
	v_pk_add_f32 v[142:143], v[142:143], 1.0 op_sel_hi:[1,0]
	v_pk_mul_f32 v[202:203], v[148:149], v[132:133]
	v_pk_mul_f32 v[192:193], v[146:147], v[142:143]
.LBB0_628:
	s_ashr_i32 s23, s22, 31
	s_lshl_b64 s[34:35], s[22:23], 20
	s_add_u32 s36, s50, s34
	v_lshl_add_u32 v0, v130, 1, v214
	s_addc_u32 s37, s51, s35
	v_lshl_add_u64 v[210:211], s[36:37], 0, v[0:1]
	v_add_co_u32_e32 v132, vcc, s73, v210
	global_load_dwordx4 v[230:233], v0, s[36:37] nt
	global_load_dwordx4 v[170:173], v0, s[36:37] offset:256 nt
	s_mov_b64 s[62:63], 0x10000
	v_addc_co_u32_e32 v133, vcc, 0, v211, vcc
	v_lshl_add_u64 v[130:131], v[210:211], 0, s[62:63]
	global_load_dwordx4 v[166:169], v[132:133], off nt
	global_load_dwordx4 v[162:165], v[130:131], off offset:256 nt
	v_add_co_u32_e32 v132, vcc, s79, v210
	s_mov_b64 s[62:63], 0x20000
	s_nop 0
	v_addc_co_u32_e32 v133, vcc, 0, v211, vcc
	s_mov_b32 s21, 0x30000
	v_lshl_add_u64 v[130:131], v[210:211], 0, s[62:63]
	global_load_dwordx4 v[158:161], v[132:133], off nt
	global_load_dwordx4 v[146:149], v[130:131], off offset:256 nt
	s_mov_b64 s[62:63], 0x30000
	v_add_co_u32_e32 v132, vcc, s21, v210
	v_lshl_add_u64 v[130:131], v[210:211], 0, s[62:63]
	s_nop 0
	v_addc_co_u32_e32 v133, vcc, 0, v211, vcc
	global_load_dwordx4 v[142:145], v[132:133], off nt
	s_nop 0
	global_load_dwordx4 v[130:133], v[130:131], off offset:256 nt
	s_add_u32 s34, s46, s34
	s_addc_u32 s35, s47, s35
	v_lshl_add_u64 v[208:209], s[34:35], 0, v[0:1]
	s_and_b64 vcc, exec, s[8:9]
	s_waitcnt vmcnt(0)
	v_cvt_f32_f16_e32 v220, v230
	v_cvt_f32_f16_sdwa v221, v230 dst_sel:DWORD dst_unused:UNUSED_PAD src0_sel:WORD_1
	v_cvt_f32_f16_e32 v230, v231
	v_cvt_f32_f16_sdwa v231, v231 dst_sel:DWORD dst_unused:UNUSED_PAD src0_sel:WORD_1
	v_cvt_f32_f16_e32 v234, v232
	v_cvt_f32_f16_e32 v236, v233
	v_cvt_f32_f16_sdwa v237, v233 dst_sel:DWORD dst_unused:UNUSED_PAD src0_sel:WORD_1
	v_cvt_f32_f16_sdwa v235, v232 dst_sel:DWORD dst_unused:UNUSED_PAD src0_sel:WORD_1
	v_pk_fma_f32 v[156:157], v[156:157], v[72:73], v[230:231]
	v_pk_fma_f32 v[154:155], v[154:155], v[70:71], v[220:221]
	v_pk_fma_f32 v[152:153], v[152:153], v[80:81], v[236:237]
	v_pk_fma_f32 v[150:151], v[150:151], v[78:79], v[234:235]
	v_cvt_pk_f16_f32 v230, v154, v155
	v_cvt_pk_f16_f32 v231, v156, v157
	v_cvt_pk_f16_f32 v232, v150, v151
	v_cvt_pk_f16_f32 v233, v152, v153
	global_store_dwordx4 v0, v[230:233], s[36:37] nt
	s_cbranch_vccnz .LBB0_630
	s_nop 0
	v_pk_mul_f32 v[230:231], v[200:201], v[154:155]
	v_pk_mul_f32 v[232:233], v[198:199], v[150:151]
	v_pk_mul_f32 v[220:221], v[204:205], v[156:157]
	v_pk_mul_f32 v[234:235], v[206:207], v[152:153]
	v_cvt_pk_bf16_f32 v230, v230, v231
	v_cvt_pk_bf16_f32 v231, v220, v221
	v_cvt_pk_bf16_f32 v232, v232, v233
	s_nop 0
	v_cvt_pk_bf16_f32 v233, v234, v235
	global_store_dwordx4 v[208:209], v[230:233], off

.LBB0_744:
	s_add_u32 s44, s38, 0x100
	s_addc_u32 s45, s39, 0
	s_and_b64 s[46:47], s[46:47], exec
	s_cselect_b32 s51, s31, s45
	s_cselect_b32 s50, s88, s44
	s_cselect_b32 s47, s29, s43
	s_cselect_b32 s46, s90, s41
	s_add_i32 s93, 0, 0x10000
	s_add_i32 s94, 0, 0x14000
	v_add_u32_e32 v84, s93, v226
	v_add_u32_e32 v88, s94, v226
	ds_read_b128 v[72:75], v84
	ds_read_b128 v[76:79], v84 offset:1024
	ds_read_b128 v[80:83], v84 offset:2048
	ds_read_b128 v[84:87], v84 offset:3072
	ds_read_b128 v[154:157], v88
	ds_read_b128 v[158:161], v88 offset:1024
	ds_read_b128 v[182:185], v88 offset:2048
	ds_read_b128 v[186:189], v88 offset:3072
	v_lshl_add_u64 v[88:89], s[38:39], 0, v[180:181]
	s_add_i32 m0, s56, 0xc000
	ds_read_b128 v[190:193], v230
	ds_read_b128 v[194:197], v230 offset:1024
	ds_read_b128 v[198:201], v230 offset:2048
	ds_read_b128 v[202:205], v230 offset:3072
	ds_read_b128 v[206:209], v230 offset:4096
	ds_read_b128 v[210:213], v230 offset:5120
	ds_read_b128 v[214:217], v230 offset:6144
	ds_read_b128 v[236:239], v230 offset:7168
	global_load_lds_dwordx4 v[88:89], off
	v_lshl_add_u64 v[88:89], s[38:39], 0, v[178:179]
	s_add_i32 m0, s56, 0xe000
	s_nop 0
	global_load_lds_dwordx4 v[88:89], off
	s_waitcnt vmcnt(8)
	s_waitcnt lgkmcnt(0)
	s_barrier
	s_setprio 1
	v_mfma_f32_16x16x32_bf16 v[150:153], v[72:75], v[190:193], v[150:153]
	v_mfma_f32_16x16x32_bf16 v[146:149], v[80:83], v[190:193], v[146:149]
	v_mfma_f32_16x16x32_bf16 v[118:121], v[72:75], v[198:201], v[118:121]
	v_mfma_f32_16x16x32_bf16 v[114:117], v[80:83], v[198:201], v[114:117]
	v_mfma_f32_16x16x32_bf16 v[142:145], v[72:75], v[206:209], v[142:145]
	v_mfma_f32_16x16x32_bf16 v[134:137], v[80:83], v[206:209], v[134:137]
	v_mfma_f32_16x16x32_bf16 v[126:129], v[72:75], v[214:217], v[126:129]
	v_mfma_f32_16x16x32_bf16 v[122:125], v[80:83], v[214:217], v[122:125]
	v_mfma_f32_16x16x32_bf16 v[150:153], v[76:79], v[194:197], v[150:153]
	v_mfma_f32_16x16x32_bf16 v[146:149], v[84:87], v[194:197], v[146:149]
	v_mfma_f32_16x16x32_bf16 v[118:121], v[76:79], v[202:205], v[118:121]
	v_mfma_f32_16x16x32_bf16 v[114:117], v[84:87], v[202:205], v[114:117]
	v_mfma_f32_16x16x32_bf16 v[142:145], v[76:79], v[210:213], v[142:145]
	v_mfma_f32_16x16x32_bf16 v[134:137], v[84:87], v[210:213], v[134:137]
	v_mfma_f32_16x16x32_bf16 v[126:129], v[76:79], v[236:239], v[126:129]
	v_mfma_f32_16x16x32_bf16 v[122:125], v[84:87], v[236:239], v[122:125]
	v_mfma_f32_16x16x32_bf16 v[138:141], v[154:157], v[190:193], v[138:141]
	v_mfma_f32_16x16x32_bf16 v[130:133], v[182:185], v[190:193], v[130:133]
	v_mfma_f32_16x16x32_bf16 v[110:113], v[154:157], v[198:201], v[110:113]
	v_mfma_f32_16x16x32_bf16 v[106:109], v[182:185], v[198:201], v[106:109]
	v_mfma_f32_16x16x32_bf16 v[102:105], v[154:157], v[206:209], v[102:105]
	v_mfma_f32_16x16x32_bf16 v[98:101], v[182:185], v[206:209], v[98:101]
	v_mfma_f32_16x16x32_bf16 v[94:97], v[154:157], v[214:217], v[94:97]
	v_mfma_f32_16x16x32_bf16 v[88:91], v[182:185], v[214:217], v[90:93]
	v_mfma_f32_16x16x32_bf16 v[138:141], v[158:161], v[194:197], v[138:141]
	v_mfma_f32_16x16x32_bf16 v[130:133], v[186:189], v[194:197], v[130:133]
	v_mfma_f32_16x16x32_bf16 v[110:113], v[158:161], v[202:205], v[110:113]
	v_mfma_f32_16x16x32_bf16 v[106:109], v[186:189], v[202:205], v[106:109]
	v_mfma_f32_16x16x32_bf16 v[102:105], v[158:161], v[210:213], v[102:105]
	v_mfma_f32_16x16x32_bf16 v[98:101], v[186:189], v[210:213], v[98:101]
	v_mfma_f32_16x16x32_bf16 v[94:97], v[158:161], v[236:239], v[94:97]
	v_mfma_f32_16x16x32_bf16 v[88:91], v[186:189], v[236:239], v[88:91]
	s_setprio 0
	s_barrier
	s_add_i32 s38, s93, s55
	v_lshl_add_u64 v[220:221], s[46:47], 0, v[166:167]
	s_mov_b32 m0, s38
	ds_read_b128 v[190:193], v230 offset:16384
	ds_read_b128 v[194:197], v230 offset:17408
	ds_read_b128 v[198:201], v230 offset:18432
	ds_read_b128 v[202:205], v230 offset:19456
	ds_read_b128 v[206:209], v230 offset:20480
	ds_read_b128 v[210:213], v230 offset:21504
	ds_read_b128 v[214:217], v230 offset:22528
	ds_read_b128 v[236:239], v230 offset:23552
	global_load_lds_dwordx4 v[220:221], off
	s_add_i32 m0, s38, 0x2000
	s_add_u32 s38, s46, 0x80000
	v_lshl_add_u64 v[240:241], s[46:47], 0, v[162:163]
	s_addc_u32 s39, s47, 0
	s_add_i32 s93, s94, s55
	global_load_lds_dwordx4 v[240:241], off
	v_lshl_add_u64 v[92:93], s[38:39], 0, v[166:167]
	s_mov_b32 m0, s93
	v_lshl_add_u64 v[242:243], s[50:51], 0, v[168:169]
	global_load_lds_dwordx4 v[92:93], off
	v_lshl_add_u64 v[92:93], s[38:39], 0, v[162:163]
	s_add_i32 m0, s93, 0x2000
	v_lshl_add_u64 v[244:245], s[50:51], 0, v[164:165]
	global_load_lds_dwordx4 v[92:93], off
	s_mov_b32 m0, s56
	s_nop 0
	global_load_lds_dwordx4 v[242:243], off
	s_mov_b32 m0, s57
	s_nop 0
	global_load_lds_dwordx4 v[244:245], off
	s_waitcnt vmcnt(8)
	s_waitcnt lgkmcnt(0)
	s_barrier
	s_setprio 1
	v_mfma_f32_16x16x32_bf16 v[62:65], v[72:75], v[190:193], v[62:65]
	v_mfma_f32_16x16x32_bf16 v[58:61], v[80:83], v[190:193], v[58:61]
	v_mfma_f32_16x16x32_bf16 v[54:57], v[72:75], v[198:201], v[54:57]
	v_mfma_f32_16x16x32_bf16 v[46:49], v[80:83], v[198:201], v[46:49]
	v_mfma_f32_16x16x32_bf16 v[38:41], v[72:75], v[206:209], v[38:41]
	v_mfma_f32_16x16x32_bf16 v[30:33], v[80:83], v[206:209], v[30:33]
	v_mfma_f32_16x16x32_bf16 v[22:25], v[72:75], v[214:217], v[22:25]
	v_mfma_f32_16x16x32_bf16 v[14:17], v[80:83], v[214:217], v[14:17]
	v_mfma_f32_16x16x32_bf16 v[62:65], v[76:79], v[194:197], v[62:65]
	v_mfma_f32_16x16x32_bf16 v[58:61], v[84:87], v[194:197], v[58:61]
	v_mfma_f32_16x16x32_bf16 v[54:57], v[76:79], v[202:205], v[54:57]
	v_mfma_f32_16x16x32_bf16 v[46:49], v[84:87], v[202:205], v[46:49]
	v_mfma_f32_16x16x32_bf16 v[38:41], v[76:79], v[210:213], v[38:41]
	v_mfma_f32_16x16x32_bf16 v[30:33], v[84:87], v[210:213], v[30:33]
	v_mfma_f32_16x16x32_bf16 v[22:25], v[76:79], v[236:239], v[22:25]
	v_mfma_f32_16x16x32_bf16 v[14:17], v[84:87], v[236:239], v[14:17]
	v_mfma_f32_16x16x32_bf16 v[50:53], v[154:157], v[190:193], v[50:53]
	v_mfma_f32_16x16x32_bf16 v[42:45], v[182:185], v[190:193], v[42:45]
	v_mfma_f32_16x16x32_bf16 v[34:37], v[154:157], v[198:201], v[34:37]
	v_mfma_f32_16x16x32_bf16 v[26:29], v[182:185], v[198:201], v[26:29]
	v_mfma_f32_16x16x32_bf16 v[18:21], v[154:157], v[206:209], v[18:21]
	v_mfma_f32_16x16x32_bf16 v[10:13], v[182:185], v[206:209], v[10:13]
	v_mfma_f32_16x16x32_bf16 v[6:9], v[154:157], v[214:217], v[6:9]
	v_mfma_f32_16x16x32_bf16 v[2:5], v[182:185], v[214:217], v[2:5]
	v_mfma_f32_16x16x32_bf16 v[50:53], v[158:161], v[194:197], v[50:53]
	v_mfma_f32_16x16x32_bf16 v[42:45], v[186:189], v[194:197], v[42:45]
	v_mfma_f32_16x16x32_bf16 v[34:37], v[158:161], v[202:205], v[34:37]
	v_mfma_f32_16x16x32_bf16 v[26:29], v[186:189], v[202:205], v[26:29]
	v_mfma_f32_16x16x32_bf16 v[18:21], v[158:161], v[210:213], v[18:21]
	v_mfma_f32_16x16x32_bf16 v[10:13], v[186:189], v[210:213], v[10:13]
	v_mfma_f32_16x16x32_bf16 v[6:9], v[158:161], v[236:239], v[6:9]
	v_mfma_f32_16x16x32_bf16 v[2:5], v[186:189], v[236:239], v[2:5]
	s_setprio 0
	s_barrier
	s_add_i32 s93, 0, 0x18000
	s_add_i32 s94, 0, 0x1c000
	v_add_u32_e32 v84, s93, v226
	v_add_u32_e32 v92, s94, v226
	ds_read_b128 v[72:75], v84
	ds_read_b128 v[76:79], v84 offset:1024
	ds_read_b128 v[80:83], v84 offset:2048
	ds_read_b128 v[84:87], v84 offset:3072
	ds_read_b128 v[154:157], v92
	ds_read_b128 v[158:161], v92 offset:1024
	ds_read_b128 v[182:185], v92 offset:2048
	ds_read_b128 v[186:189], v92 offset:3072
	s_add_u32 s38, s50, 0x80000
	s_addc_u32 s39, s51, 0
	s_mov_b32 m0, s60
	v_lshl_add_u64 v[92:93], s[38:39], 0, v[168:169]
	ds_read_b128 v[190:193], v230 offset:32768
	ds_read_b128 v[194:197], v230 offset:33792
	ds_read_b128 v[198:201], v230 offset:34816
	ds_read_b128 v[202:205], v230 offset:35840
	ds_read_b128 v[206:209], v230 offset:36864
	ds_read_b128 v[210:213], v230 offset:37888
	ds_read_b128 v[214:217], v230 offset:38912
	ds_read_b128 v[236:239], v230 offset:39936
	global_load_lds_dwordx4 v[92:93], off
	v_lshl_add_u64 v[92:93], s[38:39], 0, v[164:165]
	s_mov_b32 m0, s61
	s_nop 0
	global_load_lds_dwordx4 v[92:93], off
	s_waitcnt vmcnt(8)
	s_waitcnt lgkmcnt(0)
	s_barrier
	s_setprio 1
	v_mfma_f32_16x16x32_bf16 v[150:153], v[72:75], v[190:193], v[150:153]
	v_mfma_f32_16x16x32_bf16 v[146:149], v[80:83], v[190:193], v[146:149]
	v_mfma_f32_16x16x32_bf16 v[118:121], v[72:75], v[198:201], v[118:121]
	v_mfma_f32_16x16x32_bf16 v[114:117], v[80:83], v[198:201], v[114:117]
	v_mfma_f32_16x16x32_bf16 v[142:145], v[72:75], v[206:209], v[142:145]
	v_mfma_f32_16x16x32_bf16 v[134:137], v[80:83], v[206:209], v[134:137]
	v_mfma_f32_16x16x32_bf16 v[126:129], v[72:75], v[214:217], v[126:129]
	v_mfma_f32_16x16x32_bf16 v[122:125], v[80:83], v[214:217], v[122:125]
	v_mfma_f32_16x16x32_bf16 v[150:153], v[76:79], v[194:197], v[150:153]
	v_mfma_f32_16x16x32_bf16 v[146:149], v[84:87], v[194:197], v[146:149]
	v_mfma_f32_16x16x32_bf16 v[118:121], v[76:79], v[202:205], v[118:121]
	v_mfma_f32_16x16x32_bf16 v[114:117], v[84:87], v[202:205], v[114:117]
	v_mfma_f32_16x16x32_bf16 v[142:145], v[76:79], v[210:213], v[142:145]
	v_mfma_f32_16x16x32_bf16 v[134:137], v[84:87], v[210:213], v[134:137]
	v_mfma_f32_16x16x32_bf16 v[126:129], v[76:79], v[236:239], v[126:129]
	v_mfma_f32_16x16x32_bf16 v[122:125], v[84:87], v[236:239], v[122:125]
	v_mfma_f32_16x16x32_bf16 v[138:141], v[154:157], v[190:193], v[138:141]
	v_mfma_f32_16x16x32_bf16 v[130:133], v[182:185], v[190:193], v[130:133]
	v_mfma_f32_16x16x32_bf16 v[110:113], v[154:157], v[198:201], v[110:113]
	v_mfma_f32_16x16x32_bf16 v[106:109], v[182:185], v[198:201], v[106:109]
	v_mfma_f32_16x16x32_bf16 v[102:105], v[154:157], v[206:209], v[102:105]
	v_mfma_f32_16x16x32_bf16 v[98:101], v[182:185], v[206:209], v[98:101]
	v_mfma_f32_16x16x32_bf16 v[92:95], v[154:157], v[214:217], v[94:97]
	v_mfma_f32_16x16x32_bf16 v[88:91], v[182:185], v[214:217], v[88:91]
	v_mfma_f32_16x16x32_bf16 v[138:141], v[158:161], v[194:197], v[138:141]
	v_mfma_f32_16x16x32_bf16 v[130:133], v[186:189], v[194:197], v[130:133]
	v_mfma_f32_16x16x32_bf16 v[110:113], v[158:161], v[202:205], v[110:113]
	v_mfma_f32_16x16x32_bf16 v[106:109], v[186:189], v[202:205], v[106:109]
	v_mfma_f32_16x16x32_bf16 v[102:105], v[158:161], v[210:213], v[102:105]
	v_mfma_f32_16x16x32_bf16 v[98:101], v[186:189], v[210:213], v[98:101]
	v_mfma_f32_16x16x32_bf16 v[94:97], v[158:161], v[236:239], v[92:95]
	v_mfma_f32_16x16x32_bf16 v[90:93], v[186:189], v[236:239], v[88:91]
	s_setprio 0
	s_barrier
	s_add_i32 s38, s93, s55
	v_lshl_add_u64 v[88:89], v[220:221], 0, s[96:97]
	s_mov_b32 m0, s38
	ds_read_b128 v[190:193], v230 offset:49152
	ds_read_b128 v[194:197], v230 offset:50176
	ds_read_b128 v[198:201], v230 offset:51200
	ds_read_b128 v[202:205], v230 offset:52224
	ds_read_b128 v[206:209], v230 offset:53248
	ds_read_b128 v[210:213], v230 offset:54272
	ds_read_b128 v[214:217], v230 offset:55296
	ds_read_b128 v[236:239], v230 offset:56320
	global_load_lds_dwordx4 v[88:89], off
	s_add_i32 m0, s38, 0x2000
	s_add_u32 s38, s46, 0x80080
	v_lshl_add_u64 v[88:89], v[240:241], 0, s[96:97]
	s_addc_u32 s39, s47, 0
	s_add_i32 s46, s94, s55
	global_load_lds_dwordx4 v[88:89], off
	v_lshl_add_u64 v[88:89], s[38:39], 0, v[166:167]
	s_mov_b32 m0, s46
	s_nop 0
	global_load_lds_dwordx4 v[88:89], off
	v_lshl_add_u64 v[88:89], s[38:39], 0, v[162:163]
	s_add_i32 m0, s46, 0x2000
	s_nop 0
	global_load_lds_dwordx4 v[88:89], off
	v_lshl_add_u64 v[88:89], v[242:243], 0, s[96:97]
	s_mov_b32 m0, s75
	s_nop 0
	global_load_lds_dwordx4 v[88:89], off
	v_lshl_add_u64 v[88:89], v[244:245], 0, s[96:97]
	s_mov_b32 m0, s76
	s_nop 0
	global_load_lds_dwordx4 v[88:89], off
	s_waitcnt vmcnt(8)
	s_waitcnt lgkmcnt(0)
	s_barrier
	s_setprio 1
	v_mfma_f32_16x16x32_bf16 v[62:65], v[72:75], v[190:193], v[62:65]
	v_mfma_f32_16x16x32_bf16 v[58:61], v[80:83], v[190:193], v[58:61]
	v_mfma_f32_16x16x32_bf16 v[54:57], v[72:75], v[198:201], v[54:57]
	v_mfma_f32_16x16x32_bf16 v[46:49], v[80:83], v[198:201], v[46:49]
	v_mfma_f32_16x16x32_bf16 v[38:41], v[72:75], v[206:209], v[38:41]
	v_mfma_f32_16x16x32_bf16 v[30:33], v[80:83], v[206:209], v[30:33]
	v_mfma_f32_16x16x32_bf16 v[22:25], v[72:75], v[214:217], v[22:25]
	v_mfma_f32_16x16x32_bf16 v[14:17], v[80:83], v[214:217], v[14:17]
	v_mfma_f32_16x16x32_bf16 v[62:65], v[76:79], v[194:197], v[62:65]
	v_mfma_f32_16x16x32_bf16 v[58:61], v[84:87], v[194:197], v[58:61]
	v_mfma_f32_16x16x32_bf16 v[54:57], v[76:79], v[202:205], v[54:57]
	v_mfma_f32_16x16x32_bf16 v[46:49], v[84:87], v[202:205], v[46:49]
	v_mfma_f32_16x16x32_bf16 v[38:41], v[76:79], v[210:213], v[38:41]
	v_mfma_f32_16x16x32_bf16 v[30:33], v[84:87], v[210:213], v[30:33]
	v_mfma_f32_16x16x32_bf16 v[22:25], v[76:79], v[236:239], v[22:25]
	v_mfma_f32_16x16x32_bf16 v[14:17], v[84:87], v[236:239], v[14:17]
	v_mfma_f32_16x16x32_bf16 v[50:53], v[154:157], v[190:193], v[50:53]
	v_mfma_f32_16x16x32_bf16 v[42:45], v[182:185], v[190:193], v[42:45]
	v_mfma_f32_16x16x32_bf16 v[34:37], v[154:157], v[198:201], v[34:37]
	v_mfma_f32_16x16x32_bf16 v[26:29], v[182:185], v[198:201], v[26:29]
	v_mfma_f32_16x16x32_bf16 v[18:21], v[154:157], v[206:209], v[18:21]
	v_mfma_f32_16x16x32_bf16 v[10:13], v[182:185], v[206:209], v[10:13]
	v_mfma_f32_16x16x32_bf16 v[6:9], v[154:157], v[214:217], v[6:9]
	v_mfma_f32_16x16x32_bf16 v[2:5], v[182:185], v[214:217], v[2:5]
	v_mfma_f32_16x16x32_bf16 v[50:53], v[158:161], v[194:197], v[50:53]
	v_mfma_f32_16x16x32_bf16 v[42:45], v[186:189], v[194:197], v[42:45]
	v_mfma_f32_16x16x32_bf16 v[34:37], v[158:161], v[202:205], v[34:37]
	v_mfma_f32_16x16x32_bf16 v[26:29], v[186:189], v[202:205], v[26:29]
	v_mfma_f32_16x16x32_bf16 v[18:21], v[158:161], v[210:213], v[18:21]
	v_mfma_f32_16x16x32_bf16 v[10:13], v[186:189], v[210:213], v[10:13]
	v_mfma_f32_16x16x32_bf16 v[6:9], v[158:161], v[236:239], v[6:9]
	v_mfma_f32_16x16x32_bf16 v[2:5], v[186:189], v[236:239], v[2:5]
	s_setprio 0
	s_barrier
	s_add_i32 s91, s91, 2
	s_add_u32 s41, s41, 0x100
	s_addc_u32 s43, s43, 0
	s_cmp_gt_u32 s91, 29
	s_mov_b64 s[38:39], s[44:45]
	s_cbranch_scc1 .LBB0_755

.LBB0_905:
	s_add_u32 s8, s26, 0x100
	s_addc_u32 s9, s27, 0
	s_add_i32 s61, 0, 0x10000
	s_cmpk_eq_i32 s60, 0x54
	s_cselect_b32 s31, s23, s9
	s_cselect_b32 s30, s22, s8
	v_add_u32_e32 v0, s61, v212
	s_cselect_b32 s29, s25, s21
	s_cselect_b32 s28, s24, s19
	s_add_i32 s62, 0, 0x14000
	ds_read_b128 v[66:69], v0
	ds_read_b128 v[70:73], v0 offset:1024
	ds_read_b128 v[74:77], v0 offset:2048
	ds_read_b128 v[78:81], v0 offset:3072
	v_add_u32_e32 v0, s62, v212
	ds_read_b128 v[130:133], v0
	ds_read_b128 v[142:145], v0 offset:1024
	ds_read_b128 v[146:149], v0 offset:2048
	ds_read_b128 v[158:161], v0 offset:3072
	v_lshl_add_u64 v[220:221], s[26:27], 0, v[190:191]
	s_add_i32 m0, s39, 0xc000
	ds_read_b128 v[162:165], v215
	ds_read_b128 v[166:169], v215 offset:1024
	ds_read_b128 v[170:173], v215 offset:2048
	ds_read_b128 v[192:195], v215 offset:3072
	ds_read_b128 v[196:199], v215 offset:4096
	ds_read_b128 v[200:203], v215 offset:5120
	ds_read_b128 v[204:207], v215 offset:6144
	ds_read_b128 v[208:211], v215 offset:7168
	global_load_lds_dwordx4 v[220:221], off
	v_lshl_add_u64 v[220:221], s[26:27], 0, v[188:189]
	s_add_i32 m0, s39, 0xe000
	s_nop 0
	global_load_lds_dwordx4 v[220:221], off
	s_waitcnt vmcnt(8)
	s_waitcnt lgkmcnt(0)
	s_barrier
	s_setprio 1
	v_mfma_f32_16x16x32_bf16 v[154:157], v[66:69], v[162:165], v[154:157]
	v_mfma_f32_16x16x32_bf16 v[150:153], v[74:77], v[162:165], v[150:153]
	v_mfma_f32_16x16x32_bf16 v[138:141], v[66:69], v[170:173], v[138:141]
	v_mfma_f32_16x16x32_bf16 v[134:137], v[74:77], v[170:173], v[134:137]
	v_mfma_f32_16x16x32_bf16 v[110:113], v[66:69], v[196:199], v[110:113]
	v_mfma_f32_16x16x32_bf16 v[106:109], v[74:77], v[196:199], v[106:109]
	v_mfma_f32_16x16x32_bf16 v[94:97], v[66:69], v[204:207], v[94:97]
	v_mfma_f32_16x16x32_bf16 v[90:93], v[74:77], v[204:207], v[90:93]
	v_mfma_f32_16x16x32_bf16 v[154:157], v[70:73], v[166:169], v[154:157]
	v_mfma_f32_16x16x32_bf16 v[150:153], v[78:81], v[166:169], v[150:153]
	v_mfma_f32_16x16x32_bf16 v[138:141], v[70:73], v[192:195], v[138:141]
	v_mfma_f32_16x16x32_bf16 v[134:137], v[78:81], v[192:195], v[134:137]
	v_mfma_f32_16x16x32_bf16 v[110:113], v[70:73], v[200:203], v[110:113]
	v_mfma_f32_16x16x32_bf16 v[106:109], v[78:81], v[200:203], v[106:109]
	v_mfma_f32_16x16x32_bf16 v[94:97], v[70:73], v[208:211], v[94:97]
	v_mfma_f32_16x16x32_bf16 v[90:93], v[78:81], v[208:211], v[90:93]
	v_mfma_f32_16x16x32_bf16 v[126:129], v[130:133], v[162:165], v[126:129]
	v_mfma_f32_16x16x32_bf16 v[114:117], v[146:149], v[162:165], v[114:117]
	v_mfma_f32_16x16x32_bf16 v[122:125], v[130:133], v[170:173], v[122:125]
	v_mfma_f32_16x16x32_bf16 v[118:121], v[146:149], v[170:173], v[118:121]
	v_mfma_f32_16x16x32_bf16 v[102:105], v[130:133], v[196:199], v[102:105]
	v_mfma_f32_16x16x32_bf16 v[98:101], v[146:149], v[196:199], v[98:101]
	v_mfma_f32_16x16x32_bf16 v[86:89], v[130:133], v[204:207], v[86:89]
	v_mfma_f32_16x16x32_bf16 v[82:85], v[146:149], v[204:207], v[82:85]
	v_mfma_f32_16x16x32_bf16 v[126:129], v[142:145], v[166:169], v[126:129]
	v_mfma_f32_16x16x32_bf16 v[114:117], v[158:161], v[166:169], v[114:117]
	v_mfma_f32_16x16x32_bf16 v[122:125], v[142:145], v[192:195], v[122:125]
	v_mfma_f32_16x16x32_bf16 v[118:121], v[158:161], v[192:195], v[118:121]
	v_mfma_f32_16x16x32_bf16 v[102:105], v[142:145], v[200:203], v[102:105]
	v_mfma_f32_16x16x32_bf16 v[98:101], v[158:161], v[200:203], v[98:101]
	v_mfma_f32_16x16x32_bf16 v[86:89], v[142:145], v[208:211], v[86:89]
	v_mfma_f32_16x16x32_bf16 v[82:85], v[158:161], v[208:211], v[82:85]
	s_setprio 0
	s_barrier
	s_add_i32 s26, s61, s38
	v_lshl_add_u64 v[220:221], s[28:29], 0, v[182:183]
	s_mov_b32 m0, s26
	ds_read_b128 v[162:165], v215 offset:16384
	ds_read_b128 v[166:169], v215 offset:17408
	ds_read_b128 v[170:173], v215 offset:18432
	ds_read_b128 v[192:195], v215 offset:19456
	ds_read_b128 v[196:199], v215 offset:20480
	ds_read_b128 v[200:203], v215 offset:21504
	ds_read_b128 v[204:207], v215 offset:22528
	ds_read_b128 v[208:211], v215 offset:23552
	global_load_lds_dwordx4 v[220:221], off
	s_add_i32 m0, s26, 0x2000
	s_add_u32 s26, s28, 0x160000
	v_lshl_add_u64 v[230:231], s[28:29], 0, v[178:179]
	s_addc_u32 s27, s29, 0
	s_add_i32 s61, s62, s38
	global_load_lds_dwordx4 v[230:231], off
	v_lshl_add_u64 v[232:233], s[26:27], 0, v[182:183]
	s_mov_b32 m0, s61
	v_lshl_add_u64 v[234:235], s[30:31], 0, v[180:181]
	global_load_lds_dwordx4 v[232:233], off
	v_lshl_add_u64 v[232:233], s[26:27], 0, v[178:179]
	s_add_i32 m0, s61, 0x2000
	s_nop 0
	global_load_lds_dwordx4 v[232:233], off
	v_lshl_add_u64 v[232:233], s[30:31], 0, v[184:185]
	s_mov_b32 m0, s39
	s_nop 0
	global_load_lds_dwordx4 v[232:233], off
	s_mov_b32 m0, s40
	s_nop 0
	global_load_lds_dwordx4 v[234:235], off
	s_waitcnt vmcnt(8)
	s_waitcnt lgkmcnt(0)
	s_barrier
	s_setprio 1
	v_mfma_f32_16x16x32_bf16 v[62:65], v[66:69], v[162:165], v[62:65]
	v_mfma_f32_16x16x32_bf16 v[58:61], v[74:77], v[162:165], v[58:61]
	v_mfma_f32_16x16x32_bf16 v[46:49], v[66:69], v[170:173], v[46:49]
	v_mfma_f32_16x16x32_bf16 v[42:45], v[74:77], v[170:173], v[42:45]
	v_mfma_f32_16x16x32_bf16 v[30:33], v[66:69], v[196:199], v[30:33]
	v_mfma_f32_16x16x32_bf16 v[26:29], v[74:77], v[196:199], v[26:29]
	v_mfma_f32_16x16x32_bf16 v[14:17], v[66:69], v[204:207], v[14:17]
	v_mfma_f32_16x16x32_bf16 v[10:13], v[74:77], v[204:207], v[10:13]
	v_mfma_f32_16x16x32_bf16 v[62:65], v[70:73], v[166:169], v[62:65]
	v_mfma_f32_16x16x32_bf16 v[58:61], v[78:81], v[166:169], v[58:61]
	v_mfma_f32_16x16x32_bf16 v[46:49], v[70:73], v[192:195], v[46:49]
	v_mfma_f32_16x16x32_bf16 v[42:45], v[78:81], v[192:195], v[42:45]
	v_mfma_f32_16x16x32_bf16 v[30:33], v[70:73], v[200:203], v[30:33]
	v_mfma_f32_16x16x32_bf16 v[26:29], v[78:81], v[200:203], v[26:29]
	v_mfma_f32_16x16x32_bf16 v[14:17], v[70:73], v[208:211], v[14:17]
	v_mfma_f32_16x16x32_bf16 v[10:13], v[78:81], v[208:211], v[10:13]
	v_mfma_f32_16x16x32_bf16 v[54:57], v[130:133], v[162:165], v[54:57]
	v_mfma_f32_16x16x32_bf16 v[50:53], v[146:149], v[162:165], v[50:53]
	v_mfma_f32_16x16x32_bf16 v[38:41], v[130:133], v[170:173], v[38:41]
	v_mfma_f32_16x16x32_bf16 v[34:37], v[146:149], v[170:173], v[34:37]
	v_mfma_f32_16x16x32_bf16 v[22:25], v[130:133], v[196:199], v[22:25]
	v_mfma_f32_16x16x32_bf16 v[18:21], v[146:149], v[196:199], v[18:21]
	v_mfma_f32_16x16x32_bf16 v[6:9], v[130:133], v[204:207], v[6:9]
	v_mfma_f32_16x16x32_bf16 v[2:5], v[146:149], v[204:207], v[2:5]
	v_mfma_f32_16x16x32_bf16 v[54:57], v[142:145], v[166:169], v[54:57]
	v_mfma_f32_16x16x32_bf16 v[50:53], v[158:161], v[166:169], v[50:53]
	v_mfma_f32_16x16x32_bf16 v[38:41], v[142:145], v[192:195], v[38:41]
	v_mfma_f32_16x16x32_bf16 v[34:37], v[158:161], v[192:195], v[34:37]
	v_mfma_f32_16x16x32_bf16 v[22:25], v[142:145], v[200:203], v[22:25]
	v_mfma_f32_16x16x32_bf16 v[18:21], v[158:161], v[200:203], v[18:21]
	v_mfma_f32_16x16x32_bf16 v[6:9], v[142:145], v[208:211], v[6:9]
	v_mfma_f32_16x16x32_bf16 v[2:5], v[158:161], v[208:211], v[2:5]
	s_setprio 0
	s_barrier
	s_add_i32 s61, 0, 0x18000
	v_add_u32_e32 v0, s61, v212
	s_add_i32 s62, 0, 0x1c000
	ds_read_b128 v[66:69], v0
	ds_read_b128 v[70:73], v0 offset:1024
	ds_read_b128 v[74:77], v0 offset:2048
	ds_read_b128 v[78:81], v0 offset:3072
	v_add_u32_e32 v0, s62, v212
	ds_read_b128 v[130:133], v0
	ds_read_b128 v[142:145], v0 offset:1024
	ds_read_b128 v[146:149], v0 offset:2048
	ds_read_b128 v[158:161], v0 offset:3072
	s_add_u32 s26, s30, 0x160000
	s_addc_u32 s27, s31, 0
	s_mov_b32 m0, s41
	v_lshl_add_u64 v[236:237], s[26:27], 0, v[184:185]
	ds_read_b128 v[162:165], v215 offset:32768
	ds_read_b128 v[166:169], v215 offset:33792
	ds_read_b128 v[170:173], v215 offset:34816
	ds_read_b128 v[192:195], v215 offset:35840
	ds_read_b128 v[196:199], v215 offset:36864
	ds_read_b128 v[200:203], v215 offset:37888
	ds_read_b128 v[204:207], v215 offset:38912
	ds_read_b128 v[208:211], v215 offset:39936
	global_load_lds_dwordx4 v[236:237], off
	v_lshl_add_u64 v[236:237], s[26:27], 0, v[180:181]
	s_mov_b32 m0, s42
	s_nop 0
	global_load_lds_dwordx4 v[236:237], off
	s_waitcnt vmcnt(8)
	s_waitcnt lgkmcnt(0)
	s_barrier
	s_setprio 1
	v_mfma_f32_16x16x32_bf16 v[154:157], v[66:69], v[162:165], v[154:157]
	v_mfma_f32_16x16x32_bf16 v[150:153], v[74:77], v[162:165], v[150:153]
	v_mfma_f32_16x16x32_bf16 v[138:141], v[66:69], v[170:173], v[138:141]
	v_mfma_f32_16x16x32_bf16 v[134:137], v[74:77], v[170:173], v[134:137]
	v_mfma_f32_16x16x32_bf16 v[110:113], v[66:69], v[196:199], v[110:113]
	v_mfma_f32_16x16x32_bf16 v[106:109], v[74:77], v[196:199], v[106:109]
	v_mfma_f32_16x16x32_bf16 v[94:97], v[66:69], v[204:207], v[94:97]
	v_mfma_f32_16x16x32_bf16 v[90:93], v[74:77], v[204:207], v[90:93]
	v_mfma_f32_16x16x32_bf16 v[154:157], v[70:73], v[166:169], v[154:157]
	v_mfma_f32_16x16x32_bf16 v[150:153], v[78:81], v[166:169], v[150:153]
	v_mfma_f32_16x16x32_bf16 v[138:141], v[70:73], v[192:195], v[138:141]
	v_mfma_f32_16x16x32_bf16 v[134:137], v[78:81], v[192:195], v[134:137]
	v_mfma_f32_16x16x32_bf16 v[110:113], v[70:73], v[200:203], v[110:113]
	v_mfma_f32_16x16x32_bf16 v[106:109], v[78:81], v[200:203], v[106:109]
	v_mfma_f32_16x16x32_bf16 v[94:97], v[70:73], v[208:211], v[94:97]
	v_mfma_f32_16x16x32_bf16 v[90:93], v[78:81], v[208:211], v[90:93]
	v_mfma_f32_16x16x32_bf16 v[126:129], v[130:133], v[162:165], v[126:129]
	v_mfma_f32_16x16x32_bf16 v[114:117], v[146:149], v[162:165], v[114:117]
	v_mfma_f32_16x16x32_bf16 v[122:125], v[130:133], v[170:173], v[122:125]
	v_mfma_f32_16x16x32_bf16 v[118:121], v[146:149], v[170:173], v[118:121]
	v_mfma_f32_16x16x32_bf16 v[102:105], v[130:133], v[196:199], v[102:105]
	v_mfma_f32_16x16x32_bf16 v[98:101], v[146:149], v[196:199], v[98:101]
	v_mfma_f32_16x16x32_bf16 v[86:89], v[130:133], v[204:207], v[86:89]
	v_mfma_f32_16x16x32_bf16 v[82:85], v[146:149], v[204:207], v[82:85]
	v_mfma_f32_16x16x32_bf16 v[126:129], v[142:145], v[166:169], v[126:129]
	v_mfma_f32_16x16x32_bf16 v[114:117], v[158:161], v[166:169], v[114:117]
	v_mfma_f32_16x16x32_bf16 v[122:125], v[142:145], v[192:195], v[122:125]
	v_mfma_f32_16x16x32_bf16 v[118:121], v[158:161], v[192:195], v[118:121]
	v_mfma_f32_16x16x32_bf16 v[102:105], v[142:145], v[200:203], v[102:105]
	v_mfma_f32_16x16x32_bf16 v[98:101], v[158:161], v[200:203], v[98:101]
	v_mfma_f32_16x16x32_bf16 v[86:89], v[142:145], v[208:211], v[86:89]
	v_mfma_f32_16x16x32_bf16 v[82:85], v[158:161], v[208:211], v[82:85]
	s_setprio 0
	s_barrier
	s_add_i32 s26, s61, s38
	v_lshl_add_u64 v[220:221], v[220:221], 0, s[96:97]
	s_mov_b32 m0, s26
	ds_read_b128 v[162:165], v215 offset:49152
	ds_read_b128 v[166:169], v215 offset:50176
	ds_read_b128 v[170:173], v215 offset:51200
	ds_read_b128 v[192:195], v215 offset:52224
	ds_read_b128 v[196:199], v215 offset:53248
	ds_read_b128 v[200:203], v215 offset:54272
	ds_read_b128 v[204:207], v215 offset:55296
	ds_read_b128 v[208:211], v215 offset:56320
	global_load_lds_dwordx4 v[220:221], off
	s_add_i32 m0, s26, 0x2000
	s_add_u32 s26, s28, 0x160080
	v_lshl_add_u64 v[220:221], v[230:231], 0, s[96:97]
	s_addc_u32 s27, s29, 0
	s_add_i32 s28, s62, s38
	global_load_lds_dwordx4 v[220:221], off
	v_lshl_add_u64 v[220:221], s[26:27], 0, v[182:183]
	s_mov_b32 m0, s28
	s_nop 0
	global_load_lds_dwordx4 v[220:221], off
	v_lshl_add_u64 v[220:221], s[26:27], 0, v[178:179]
	s_add_i32 m0, s28, 0x2000
	s_nop 0
	global_load_lds_dwordx4 v[220:221], off
	v_lshl_add_u64 v[220:221], v[232:233], 0, s[96:97]
	s_mov_b32 m0, s54
	s_nop 0
	global_load_lds_dwordx4 v[220:221], off
	v_lshl_add_u64 v[220:221], v[234:235], 0, s[96:97]
	s_mov_b32 m0, s55
	s_nop 0
	global_load_lds_dwordx4 v[220:221], off
	s_waitcnt vmcnt(8)
	s_waitcnt lgkmcnt(0)
	s_barrier
	s_setprio 1
	v_mfma_f32_16x16x32_bf16 v[62:65], v[66:69], v[162:165], v[62:65]
	v_mfma_f32_16x16x32_bf16 v[58:61], v[74:77], v[162:165], v[58:61]
	v_mfma_f32_16x16x32_bf16 v[46:49], v[66:69], v[170:173], v[46:49]
	v_mfma_f32_16x16x32_bf16 v[42:45], v[74:77], v[170:173], v[42:45]
	v_mfma_f32_16x16x32_bf16 v[30:33], v[66:69], v[196:199], v[30:33]
	v_mfma_f32_16x16x32_bf16 v[26:29], v[74:77], v[196:199], v[26:29]
	v_mfma_f32_16x16x32_bf16 v[14:17], v[66:69], v[204:207], v[14:17]
	v_mfma_f32_16x16x32_bf16 v[10:13], v[74:77], v[204:207], v[10:13]
	v_mfma_f32_16x16x32_bf16 v[62:65], v[70:73], v[166:169], v[62:65]
	v_mfma_f32_16x16x32_bf16 v[58:61], v[78:81], v[166:169], v[58:61]
	v_mfma_f32_16x16x32_bf16 v[46:49], v[70:73], v[192:195], v[46:49]
	v_mfma_f32_16x16x32_bf16 v[42:45], v[78:81], v[192:195], v[42:45]
	v_mfma_f32_16x16x32_bf16 v[30:33], v[70:73], v[200:203], v[30:33]
	v_mfma_f32_16x16x32_bf16 v[26:29], v[78:81], v[200:203], v[26:29]
	v_mfma_f32_16x16x32_bf16 v[14:17], v[70:73], v[208:211], v[14:17]
	v_mfma_f32_16x16x32_bf16 v[10:13], v[78:81], v[208:211], v[10:13]
	v_mfma_f32_16x16x32_bf16 v[54:57], v[130:133], v[162:165], v[54:57]
	v_mfma_f32_16x16x32_bf16 v[50:53], v[146:149], v[162:165], v[50:53]
	v_mfma_f32_16x16x32_bf16 v[38:41], v[130:133], v[170:173], v[38:41]
	v_mfma_f32_16x16x32_bf16 v[34:37], v[146:149], v[170:173], v[34:37]
	v_mfma_f32_16x16x32_bf16 v[22:25], v[130:133], v[196:199], v[22:25]
	v_mfma_f32_16x16x32_bf16 v[18:21], v[146:149], v[196:199], v[18:21]
	v_mfma_f32_16x16x32_bf16 v[6:9], v[130:133], v[204:207], v[6:9]
	v_mfma_f32_16x16x32_bf16 v[2:5], v[146:149], v[204:207], v[2:5]
	v_mfma_f32_16x16x32_bf16 v[54:57], v[142:145], v[166:169], v[54:57]
	v_mfma_f32_16x16x32_bf16 v[50:53], v[158:161], v[166:169], v[50:53]
	v_mfma_f32_16x16x32_bf16 v[38:41], v[142:145], v[192:195], v[38:41]
	v_mfma_f32_16x16x32_bf16 v[34:37], v[158:161], v[192:195], v[34:37]
	v_mfma_f32_16x16x32_bf16 v[22:25], v[142:145], v[200:203], v[22:25]
	v_mfma_f32_16x16x32_bf16 v[18:21], v[158:161], v[200:203], v[18:21]
	v_mfma_f32_16x16x32_bf16 v[6:9], v[142:145], v[208:211], v[6:9]
	v_mfma_f32_16x16x32_bf16 v[2:5], v[158:161], v[208:211], v[2:5]
	s_setprio 0
	s_barrier
	s_add_i32 s60, s60, 2
	s_add_u32 s19, s19, 0x100
	s_addc_u32 s21, s21, 0
	s_cmpk_gt_u32 s60, 0x55
	s_mov_b64 s[26:27], s[8:9]
	s_cbranch_scc0 .LBB0_905
	s_and_b64 vcc, exec, s[16:17]
	s_cbranch_vccz .LBB0_908
	s_barrier
.LBB0_908:
	s_ashr_i32 s8, s20, 5
	v_lshl_or_b32 v130, s18, 8, v213
	s_mul_i32 s21, s8, 0xc000
	s_mul_hi_i32 s19, s8, 0xc000
	s_add_u32 s8, s47, s21
	v_ashrrev_i32_e32 v131, 31, v130
	s_addc_u32 s9, s50, s19
	v_lshlrev_b64 v[66:67], 2, v[130:131]
	v_lshl_add_u64 v[74:75], s[8:9], 0, v[66:67]
	global_load_dwordx4 v[70:73], v[74:75], off
	s_add_u32 s8, s52, s21
	s_addc_u32 s9, s53, s19
	v_cndmask_b32_e64 v0, 0, 1, s[12:13]
	v_lshl_add_u64 v[132:133], s[14:15], 0, v[66:67]
	v_lshl_add_u64 v[142:143], s[8:9], 0, v[66:67]
	v_mov_b32_e32 v198, 0
	v_cmp_ne_u32_e64 s[8:9], 1, v0
	s_andn2_b64 vcc, exec, s[12:13]
	v_mov_b32_e32 v200, 0
	v_mov_b32_e32 v201, 0
	v_mov_b32_e32 v204, 0
	v_mov_b32_e32 v205, 0
	s_cbranch_vccnz .LBB0_910
	global_load_dwordx4 v[66:69], v[142:143], off
	global_load_dwordx4 v[76:79], v[132:133], off
	s_waitcnt vmcnt(0)
	v_pk_add_f32 v[68:69], v[68:69], 1.0 op_sel_hi:[1,0]
	v_pk_add_f32 v[66:67], v[66:67], 1.0 op_sel_hi:[1,0]
	v_pk_mul_f32 v[204:205], v[78:79], v[68:69]
	v_pk_mul_f32 v[200:201], v[76:77], v[66:67]

.LBB0_912:
	global_load_dwordx4 v[66:69], v[74:75], off offset:512
	v_mov_b32_e32 v192, 0
	s_and_b64 vcc, exec, s[8:9]
	v_mov_b32_e32 v194, 0
	v_mov_b32_e32 v195, 0
	v_mov_b32_e32 v196, 0
	v_mov_b32_e32 v197, 0
	s_mov_b32 s62, 0xf000
	s_cbranch_vccnz .LBB0_914
	global_load_dwordx4 v[144:147], v[142:143], off offset:512
	global_load_dwordx4 v[158:161], v[132:133], off offset:512
	s_waitcnt vmcnt(0)
	v_pk_add_f32 v[76:77], v[146:147], 1.0 op_sel_hi:[1,0]
	v_pk_add_f32 v[144:145], v[144:145], 1.0 op_sel_hi:[1,0]
	v_pk_mul_f32 v[196:197], v[160:161], v[76:77]
	v_pk_mul_f32 v[194:195], v[158:159], v[144:145]

.LBB0_916:
	s_ashr_i32 s21, s20, 31
	s_lshl_b64 s[26:27], s[20:21], 20
	s_add_u32 s28, s45, s26
	v_lshl_add_u32 v0, v130, 1, v214
	s_addc_u32 s29, s46, s27
	v_lshl_add_u64 v[210:211], s[28:29], 0, v[0:1]
	v_add_co_u32_e32 v132, vcc, s95, v210
	global_load_dwordx4 v[230:233], v0, s[28:29] nt
	global_load_dwordx4 v[170:173], v0, s[28:29] offset:256 nt
	s_mov_b64 s[30:31], 0x10000
	v_addc_co_u32_e32 v133, vcc, 0, v211, vcc
	v_lshl_add_u64 v[130:131], v[210:211], 0, s[30:31]
	global_load_dwordx4 v[166:169], v[132:133], off nt
	global_load_dwordx4 v[162:165], v[130:131], off offset:256 nt
	v_add_co_u32_e32 v132, vcc, s79, v210
	s_mov_b64 s[30:31], 0x20000
	s_nop 0
	v_addc_co_u32_e32 v133, vcc, 0, v211, vcc
	s_mov_b32 s19, 0x30000
	v_lshl_add_u64 v[130:131], v[210:211], 0, s[30:31]
	global_load_dwordx4 v[158:161], v[132:133], off nt
	global_load_dwordx4 v[146:149], v[130:131], off offset:256 nt
	s_mov_b64 s[30:31], 0x30000
	v_add_co_u32_e32 v132, vcc, s19, v210
	v_lshl_add_u64 v[130:131], v[210:211], 0, s[30:31]
	s_nop 0
	v_addc_co_u32_e32 v133, vcc, 0, v211, vcc
	global_load_dwordx4 v[142:145], v[132:133], off nt
	s_nop 0
	global_load_dwordx4 v[130:133], v[130:131], off offset:256 nt
	s_add_u32 s26, s43, s26
	s_addc_u32 s27, s44, s27
	v_lshl_add_u64 v[208:209], s[26:27], 0, v[0:1]
	s_and_b64 vcc, exec, s[8:9]
	s_waitcnt vmcnt(0)
	v_cvt_f32_f16_e32 v220, v230
	v_cvt_f32_f16_sdwa v221, v230 dst_sel:DWORD dst_unused:UNUSED_PAD src0_sel:WORD_1
	v_cvt_f32_f16_e32 v230, v231
	v_cvt_f32_f16_sdwa v231, v231 dst_sel:DWORD dst_unused:UNUSED_PAD src0_sel:WORD_1
	v_cvt_f32_f16_e32 v234, v232
	v_cvt_f32_f16_e32 v236, v233
	v_cvt_f32_f16_sdwa v237, v233 dst_sel:DWORD dst_unused:UNUSED_PAD src0_sel:WORD_1
	v_cvt_f32_f16_sdwa v235, v232 dst_sel:DWORD dst_unused:UNUSED_PAD src0_sel:WORD_1
	v_pk_fma_f32 v[156:157], v[156:157], v[72:73], v[230:231]
	v_pk_fma_f32 v[154:155], v[154:155], v[70:71], v[220:221]
	v_pk_fma_f32 v[152:153], v[152:153], v[80:81], v[236:237]
	v_pk_fma_f32 v[150:151], v[150:151], v[78:79], v[234:235]
	v_cvt_pk_f16_f32 v230, v154, v155
	v_cvt_pk_f16_f32 v231, v156, v157
	v_cvt_pk_f16_f32 v232, v150, v151
	v_cvt_pk_f16_f32 v233, v152, v153
	global_store_dwordx4 v0, v[230:233], s[28:29] nt
	s_cbranch_vccnz .LBB0_918
	s_nop 0
	v_pk_mul_f32 v[230:231], v[200:201], v[154:155]
	v_pk_mul_f32 v[232:233], v[198:199], v[150:151]
	v_pk_mul_f32 v[220:221], v[204:205], v[156:157]
	v_pk_mul_f32 v[234:235], v[206:207], v[152:153]
	v_cvt_pk_bf16_f32 v230, v230, v231
	v_cvt_pk_bf16_f32 v231, v220, v221
	v_cvt_pk_bf16_f32 v232, v232, v233
	s_nop 0
	v_cvt_pk_bf16_f32 v233, v234, v235
	global_store_dwordx4 v[208:209], v[230:233], off

	.amdhsa_kernel _Z9hymba_fwd4Args
		.amdhsa_group_segment_fixed_size 0
		.amdhsa_private_segment_fixed_size 0
		.amdhsa_kernarg_size 440
		.amdhsa_user_sgpr_count 2
		.amdhsa_user_sgpr_dispatch_ptr 0
		.amdhsa_user_sgpr_queue_ptr 0
		.amdhsa_user_sgpr_kernarg_segment_ptr 1
		.amdhsa_user_sgpr_dispatch_id 0
		.amdhsa_user_sgpr_kernarg_preload_length 0
		.amdhsa_user_sgpr_kernarg_preload_offset 0
		.amdhsa_user_sgpr_private_segment_size 0
		.amdhsa_uses_dynamic_stack 0
		.amdhsa_enable_private_segment 0
		.amdhsa_system_sgpr_workgroup_id_x 1
		.amdhsa_system_sgpr_workgroup_id_y 0
		.amdhsa_system_sgpr_workgroup_id_z 0
		.amdhsa_system_sgpr_workgroup_info 0
		.amdhsa_system_vgpr_workitem_id 0
		.amdhsa_next_free_vgpr 256
		.amdhsa_next_free_sgpr 98
		.amdhsa_accum_offset 256
		.amdhsa_reserve_vcc 1
		.amdhsa_float_round_mode_32 0
		.amdhsa_float_round_mode_16_64 0
		.amdhsa_float_denorm_mode_32 3
		.amdhsa_float_denorm_mode_16_64 3
		.amdhsa_dx10_clamp 1
		.amdhsa_ieee_mode 1
		.amdhsa_fp16_overflow 0
		.amdhsa_tg_split 0
		.amdhsa_exception_fp_ieee_invalid_op 0
		.amdhsa_exception_fp_denorm_src 0
		.amdhsa_exception_fp_ieee_div_zero 0
		.amdhsa_exception_fp_ieee_overflow 0
		.amdhsa_exception_fp_ieee_underflow 0
		.amdhsa_exception_fp_ieee_inexact 0
		.amdhsa_exception_int_div_zero 0
	.end_amdhsa_kernel

amdhsa.kernels:
  - .agpr_count:     0
    .args:
      - .offset:         0
        .size:           184
        .value_kind:     by_value
      - .offset:         184
        .size:           4
        .value_kind:     hidden_block_count_x
      - .offset:         188
        .size:           4
        .value_kind:     hidden_block_count_y
      - .offset:         192
        .size:           4
        .value_kind:     hidden_block_count_z
      - .offset:         196
        .size:           2
        .value_kind:     hidden_group_size_x
      - .offset:         198
        .size:           2
        .value_kind:     hidden_group_size_y
      - .offset:         200
        .size:           2
        .value_kind:     hidden_group_size_z
      - .offset:         202
        .size:           2
        .value_kind:     hidden_remainder_x
      - .offset:         204
        .size:           2
        .value_kind:     hidden_remainder_y
      - .offset:         206
        .size:           2
        .value_kind:     hidden_remainder_z
      - .offset:         224
        .size:           8
        .value_kind:     hidden_global_offset_x
      - .offset:         232
        .size:           8
        .value_kind:     hidden_global_offset_y
      - .offset:         240
        .size:           8
        .value_kind:     hidden_global_offset_z
      - .offset:         248
        .size:           2
        .value_kind:     hidden_grid_dims
      - .offset:         304
        .size:           4
        .value_kind:     hidden_dynamic_lds_size
    .group_segment_fixed_size: 0
    .kernarg_segment_align: 8
    .kernarg_segment_size: 440
    .language:       OpenCL C
    .language_version:
      - 2
      - 0
    .max_flat_workgroup_size: 512
    .name:           _Z9hymba_fwd4Args
    .private_segment_fixed_size: 0
    .sgpr_count:     104
    .sgpr_spill_count: 118
    .symbol:         _Z9hymba_fwd4Args.kd
    .uniform_work_group_size: 1
    .uses_dynamic_stack: false
    .vgpr_count:     256
    .vgpr_spill_count: 0
    .wavefront_size: 64
